# GEMM K-loops: 24 LDS-DMA loads switched to SGPR-base + 32-bit VGPR offset form, dropping their 64-bit VALU address adds (on top of v48)
# baseline (speedup 1.0000x reference)
; #define PG8_STAGE(bufoff, gbase, voff) do { _Pragma("unroll") for (int _i = 0; _i < 2; ++_i) \
;         __builtin_amdgcn_global_load_lds((const unsigned*)((const char*)(gbase) + (voff)[_i]), (LAS unsigned*)(lds + (bufoff) + ldsw + _i * 8192), 16, 0, 0); } while (0)
; #define PG8_LDA(dst, b, h) do { _Pragma("unroll") for (int m = 0; m < 4; ++m) _Pragma("unroll") for (int k = 0; k < 2; ++k) dst[m][k] = *(const LAS bf16x8*)(lds + PG8_SA(b, h) + aoff + m * 2048 + k * 1024); } while (0)
; #define PG8_LDB(dst, b, h) do { _Pragma("unroll") for (int n = 0; n < 2; ++n) _Pragma("unroll") for (int k = 0; k < 2; ++k) dst[n][k] = *(const LAS bf16x8*)(lds + PG8_SB(b, h) + boff + n * 2048 + k * 1024); } while (0)
; #define PG8_MMA(ai, bj, At, Bt) do { __builtin_amdgcn_s_setprio(1); _Pragma("unroll") for (int m = 0; m < 4; ++m) _Pragma("unroll") for (int n = 0; n < 2; ++n) _Pragma("unroll") for (int k = 0; k < 2; ++k) \
;         acc[ai][bj][m][n] = __builtin_amdgcn_mfma_f32_16x16x32_bf16(Bt[n][k], At[m][k], acc[ai][bj][m][n], 0, 0, 0); __builtin_amdgcn_s_setprio(0); } while (0)
; #define PG8_WAIT_V(n) asm volatile("s_waitcnt vmcnt(" #n ")" ::: "memory")
; #define PG8_WAIT_L(n) asm volatile("s_waitcnt lgkmcnt(" #n ")" ::: "memory")
; template <class Epi, class Sched, bool ALIGN_EPI = false, bool SP2 = false>
; __device__ __forceinline__ void gemm_phase(LAS unsigned char* lds, const Gemm g, const Sched& S, const Epi& E) {
;     ...
;         for (int t = 0; t < nt; t += 2) {
;             const bool last = (t == nt - 2);
;             const char* a1 = cA + (size_t)(t + 1) * kstep;
;             const char* a2 = last ? nA : cA + (size_t)(t + 2) * kstep; const char* b2 = last ? nB : cB + (size_t)(t + 2) * kstep;
;             const char* a3 = a2 + kstep; const char* b3 = b2 + kstep;
;             if (last && has_next) S.a_ready(nxt);
;             if constexpr (SP2) {
;             PG8_LDB(B0, 0, 0); PG8_LDB(B1, 0, 1); PG8_SCHED; PG8_LDA(At, 0, 0); PG8_STAGE(PG8_SA(1, 1), a1 + hstep, voffA);
;             PG8_WAIT_V(8); PG8_WAIT_L(0); PG8_BAR; PG8_MMA(0, 0, At, B0); PG8_MMA(0, 1, At, B1); PG8_BAR; PG8_SCHED;
;             PG8_LDA(At, 0, 1); PG8_STAGE(PG8_SB(0, 0), b2, voffB); PG8_STAGE(PG8_SB(0, 1), b2 + hstep, voffB); PG8_STAGE(PG8_SA(0, 0), a2, voffA);
;             PG8_WAIT_V(8); PG8_WAIT_L(0); PG8_BAR; PG8_MMA(1, 0, At, B0); PG8_MMA(1, 1, At, B1); PG8_BAR; PG8_SCHED;
.LBB0_41:
	v_or_b32_e32 v144, 0x10000, v142
	v_add_u32_e32 v148, 0x10400, v142
	v_add_u32_e32 v152, 0x10800, v142
	v_add_u32_e32 v156, 0x10c00, v142
	v_or_b32_e32 v160, 0x14000, v142
	v_add_u32_e32 v164, 0x14400, v142
	v_add_u32_e32 v168, 0x14800, v142
	ds_read_b128 v[144:147], v144
	ds_read_b128 v[148:151], v148
	ds_read_b128 v[152:155], v152
	ds_read_b128 v[156:159], v156
	ds_read_b128 v[160:163], v160
	ds_read_b128 v[164:167], v164
	v_add_u32_e32 v169, 0x14c00, v142
	ds_read_b128 v[172:175], v168
	ds_read_b128 v[176:179], v169
	s_add_u32 s44, s42, 0x100
	s_addc_u32 s45, s43, 0
	s_cmp_eq_u32 s71, 38
	s_cselect_b32 s49, s1, s45
	s_cselect_b32 s48, s0, s44
	s_cselect_b32 s47, s41, s70
	s_cselect_b32 s46, s40, s69
	s_mov_b32 m0, s64
	ds_read_b128 v[180:183], v141
	ds_read_b128 v[184:187], v141 offset:1024
	ds_read_b128 v[188:191], v141 offset:2048
	ds_read_b128 v[192:195], v141 offset:3072
	ds_read_b128 v[208:211], v141 offset:4096
	ds_read_b128 v[212:215], v141 offset:5120
	ds_read_b128 v[216:219], v141 offset:6144
	ds_read_b128 v[220:223], v141 offset:7168
	global_load_lds_dwordx4 v136, s[42:43]
	s_mov_b32 m0, s65
	s_nop 0
	global_load_lds_dwordx4 v138, s[42:43]
	s_waitcnt vmcnt(8)
	s_waitcnt lgkmcnt(0)
	s_barrier
	s_setprio 1
	s_waitcnt lgkmcnt(0)
	v_mfma_f32_16x16x32_bf16 v[124:127], v[144:147], v[180:183], v[124:127]
	v_mfma_f32_16x16x32_bf16 v[120:123], v[152:155], v[180:183], v[120:123]
	v_mfma_f32_16x16x32_bf16 v[116:119], v[144:147], v[188:191], v[116:119]
	v_mfma_f32_16x16x32_bf16 v[112:115], v[152:155], v[188:191], v[112:115]
	v_mfma_f32_16x16x32_bf16 v[100:103], v[144:147], v[208:211], v[100:103]
	v_mfma_f32_16x16x32_bf16 v[96:99], v[152:155], v[208:211], v[96:99]
	v_mfma_f32_16x16x32_bf16 v[84:87], v[144:147], v[216:219], v[84:87]
	v_mfma_f32_16x16x32_bf16 v[80:83], v[152:155], v[216:219], v[80:83]
	v_mfma_f32_16x16x32_bf16 v[124:127], v[148:151], v[184:187], v[124:127]
	v_mfma_f32_16x16x32_bf16 v[120:123], v[156:159], v[184:187], v[120:123]
	v_mfma_f32_16x16x32_bf16 v[116:119], v[148:151], v[192:195], v[116:119]
	v_mfma_f32_16x16x32_bf16 v[112:115], v[156:159], v[192:195], v[112:115]
	v_mfma_f32_16x16x32_bf16 v[100:103], v[148:151], v[212:215], v[100:103]
	v_mfma_f32_16x16x32_bf16 v[96:99], v[156:159], v[212:215], v[96:99]
	v_mfma_f32_16x16x32_bf16 v[84:87], v[148:151], v[220:223], v[84:87]
	v_mfma_f32_16x16x32_bf16 v[80:83], v[156:159], v[220:223], v[80:83]
	s_setprio 0
	s_setprio 1
	v_mfma_f32_16x16x32_bf16 v[108:111], v[160:163], v[180:183], v[108:111]
	v_mfma_f32_16x16x32_bf16 v[104:107], v[172:175], v[180:183], v[104:107]
	v_mfma_f32_16x16x32_bf16 v[92:95], v[160:163], v[188:191], v[92:95]
	v_mfma_f32_16x16x32_bf16 v[88:91], v[172:175], v[188:191], v[88:91]
	v_mfma_f32_16x16x32_bf16 v[76:79], v[160:163], v[208:211], v[76:79]
	v_mfma_f32_16x16x32_bf16 v[72:75], v[172:175], v[208:211], v[72:75]
	v_mfma_f32_16x16x32_bf16 v[68:71], v[160:163], v[216:219], v[68:71]
	v_mfma_f32_16x16x32_bf16 v[64:67], v[172:175], v[216:219], v[64:67]
	v_mfma_f32_16x16x32_bf16 v[108:111], v[164:167], v[184:187], v[108:111]
	v_mfma_f32_16x16x32_bf16 v[104:107], v[176:179], v[184:187], v[104:107]
	v_mfma_f32_16x16x32_bf16 v[92:95], v[164:167], v[192:195], v[92:95]
	v_mfma_f32_16x16x32_bf16 v[88:91], v[176:179], v[192:195], v[88:91]
	v_mfma_f32_16x16x32_bf16 v[76:79], v[164:167], v[212:215], v[76:79]
	v_mfma_f32_16x16x32_bf16 v[72:75], v[176:179], v[212:215], v[72:75]
	v_mfma_f32_16x16x32_bf16 v[68:71], v[164:167], v[220:223], v[68:71]
	v_mfma_f32_16x16x32_bf16 v[64:67], v[176:179], v[220:223], v[64:67]
	s_setprio 0
	s_barrier
	s_mov_b32 m0, s27
	v_lshl_add_u64 v[168:169], s[46:47], 0, v[128:129]
	s_add_u32 s42, s46, 0xa8000
	ds_read_b128 v[180:183], v141 offset:16384
	ds_read_b128 v[184:187], v141 offset:17408
	ds_read_b128 v[188:191], v141 offset:18432
	ds_read_b128 v[192:195], v141 offset:19456
	ds_read_b128 v[208:211], v141 offset:20480
	ds_read_b128 v[212:215], v141 offset:21504
	ds_read_b128 v[216:219], v141 offset:22528
	ds_read_b128 v[220:223], v141 offset:23552
	global_load_lds_dwordx4 v[168:169], off
	v_lshl_add_u64 v[196:197], s[46:47], 0, v[130:131]
	s_mov_b32 m0, s30
	s_addc_u32 s43, s47, 0
	global_load_lds_dwordx4 v[196:197], off
	s_mov_b32 m0, s31
	v_lshl_add_u64 v[224:225], s[48:49], 0, v[132:133]
	s_nop 4
	global_load_lds_dwordx4 v128, s[42:43]
	s_mov_b32 m0, s50
	s_nop 0
	global_load_lds_dwordx4 v130, s[42:43]
	v_lshl_add_u64 v[200:201], s[48:49], 0, v[134:135]
	s_mov_b32 m0, s26
	s_nop 0
	global_load_lds_dwordx4 v[200:201], off
	s_mov_b32 m0, s51
	s_nop 0
	global_load_lds_dwordx4 v[224:225], off
	s_waitcnt vmcnt(8)
	s_waitcnt lgkmcnt(0)
	s_barrier
; #define PG8_STAGE(bufoff, gbase, voff) do { _Pragma("unroll") for (int _i = 0; _i < 2; ++_i) \
;         __builtin_amdgcn_global_load_lds((const unsigned*)((const char*)(gbase) + (voff)[_i]), (LAS unsigned*)(lds + (bufoff) + ldsw + _i * 8192), 16, 0, 0); } while (0)
; #define PG8_LDA(dst, b, h) do { _Pragma("unroll") for (int m = 0; m < 4; ++m) _Pragma("unroll") for (int k = 0; k < 2; ++k) dst[m][k] = *(const LAS bf16x8*)(lds + PG8_SA(b, h) + aoff + m * 2048 + k * 1024); } while (0)
; #define PG8_LDB(dst, b, h) do { _Pragma("unroll") for (int n = 0; n < 2; ++n) _Pragma("unroll") for (int k = 0; k < 2; ++k) dst[n][k] = *(const LAS bf16x8*)(lds + PG8_SB(b, h) + boff + n * 2048 + k * 1024); } while (0)
; #define PG8_MMA(ai, bj, At, Bt) do { __builtin_amdgcn_s_setprio(1); _Pragma("unroll") for (int m = 0; m < 4; ++m) _Pragma("unroll") for (int n = 0; n < 2; ++n) _Pragma("unroll") for (int k = 0; k < 2; ++k) \
;         acc[ai][bj][m][n] = __builtin_amdgcn_mfma_f32_16x16x32_bf16(Bt[n][k], At[m][k], acc[ai][bj][m][n], 0, 0, 0); __builtin_amdgcn_s_setprio(0); } while (0)
; #define PG8_WAIT_V(n) asm volatile("s_waitcnt vmcnt(" #n ")" ::: "memory")
; #define PG8_WAIT_L(n) asm volatile("s_waitcnt lgkmcnt(" #n ")" ::: "memory")
; #define PG8_BAR __builtin_amdgcn_s_barrier()
; #define PG8_SCHED __builtin_amdgcn_sched_barrier(0)
; template <class Epi, class Sched, bool ALIGN_EPI = false, bool SP2 = false>
; __device__ __forceinline__ void gemm_phase(LAS unsigned char* lds, const Gemm g, const Sched& S, const Epi& E) {
;     ...
;             PG8_LDA(At, 0, 1); PG8_STAGE(PG8_SB(0, 0), b2, voffB); PG8_STAGE(PG8_SB(0, 1), b2 + hstep, voffB); PG8_STAGE(PG8_SA(0, 0), a2, voffA);
;             PG8_WAIT_V(8); PG8_WAIT_L(0); PG8_BAR; PG8_MMA(1, 0, At, B0); PG8_MMA(1, 1, At, B1); PG8_BAR; PG8_SCHED;
;             PG8_LDB(B0, 1, 0); PG8_LDB(B1, 1, 1); PG8_SCHED; PG8_LDA(At, 1, 0); PG8_STAGE(PG8_SA(0, 1), a2 + hstep, voffA);
;             PG8_WAIT_V(8); PG8_WAIT_L(0); PG8_BAR; PG8_MMA(0, 0, At, B0); PG8_MMA(0, 1, At, B1); PG8_BAR; PG8_SCHED;
;             PG8_LDA(At, 1, 1); PG8_STAGE(PG8_SB(1, 0), b3, voffB); PG8_STAGE(PG8_SB(1, 1), b3 + hstep, voffB); PG8_STAGE(PG8_SA(1, 0), a3, voffA);
	s_setprio 1
	s_waitcnt lgkmcnt(0)
	v_mfma_f32_16x16x32_bf16 v[60:63], v[144:147], v[180:183], v[60:63]
	v_mfma_f32_16x16x32_bf16 v[56:59], v[152:155], v[180:183], v[56:59]
	v_mfma_f32_16x16x32_bf16 v[52:55], v[144:147], v[188:191], v[52:55]
	v_mfma_f32_16x16x32_bf16 v[48:51], v[152:155], v[188:191], v[48:51]
	v_mfma_f32_16x16x32_bf16 v[36:39], v[144:147], v[208:211], v[36:39]
	v_mfma_f32_16x16x32_bf16 v[32:35], v[152:155], v[208:211], v[32:35]
	v_mfma_f32_16x16x32_bf16 v[20:23], v[144:147], v[216:219], v[20:23]
	v_mfma_f32_16x16x32_bf16 v[16:19], v[152:155], v[216:219], v[16:19]
	v_mfma_f32_16x16x32_bf16 v[60:63], v[148:151], v[184:187], v[60:63]
	v_mfma_f32_16x16x32_bf16 v[56:59], v[156:159], v[184:187], v[56:59]
	v_mfma_f32_16x16x32_bf16 v[52:55], v[148:151], v[192:195], v[52:55]
	v_mfma_f32_16x16x32_bf16 v[48:51], v[156:159], v[192:195], v[48:51]
	v_mfma_f32_16x16x32_bf16 v[36:39], v[148:151], v[212:215], v[36:39]
	v_mfma_f32_16x16x32_bf16 v[32:35], v[156:159], v[212:215], v[32:35]
	v_mfma_f32_16x16x32_bf16 v[20:23], v[148:151], v[220:223], v[20:23]
	v_mfma_f32_16x16x32_bf16 v[16:19], v[156:159], v[220:223], v[16:19]
	s_setprio 0
	s_setprio 1
	v_mfma_f32_16x16x32_bf16 v[44:47], v[160:163], v[180:183], v[44:47]
	v_mfma_f32_16x16x32_bf16 v[40:43], v[172:175], v[180:183], v[40:43]
	v_mfma_f32_16x16x32_bf16 v[28:31], v[160:163], v[188:191], v[28:31]
	v_mfma_f32_16x16x32_bf16 v[24:27], v[172:175], v[188:191], v[24:27]
	v_mfma_f32_16x16x32_bf16 v[12:15], v[160:163], v[208:211], v[12:15]
	v_mfma_f32_16x16x32_bf16 v[8:11], v[172:175], v[208:211], v[8:11]
	v_mfma_f32_16x16x32_bf16 v[4:7], v[160:163], v[216:219], v[4:7]
	v_mfma_f32_16x16x32_bf16 v[0:3], v[172:175], v[216:219], v[0:3]
	v_mfma_f32_16x16x32_bf16 v[44:47], v[164:167], v[184:187], v[44:47]
	v_mfma_f32_16x16x32_bf16 v[40:43], v[176:179], v[184:187], v[40:43]
	v_mfma_f32_16x16x32_bf16 v[28:31], v[164:167], v[192:195], v[28:31]
	v_mfma_f32_16x16x32_bf16 v[24:27], v[176:179], v[192:195], v[24:27]
	v_mfma_f32_16x16x32_bf16 v[12:15], v[164:167], v[212:215], v[12:15]
	v_mfma_f32_16x16x32_bf16 v[8:11], v[176:179], v[212:215], v[8:11]
	v_mfma_f32_16x16x32_bf16 v[4:7], v[164:167], v[220:223], v[4:7]
	v_mfma_f32_16x16x32_bf16 v[0:3], v[176:179], v[220:223], v[0:3]
	s_setprio 0
	s_barrier
	v_or_b32_e32 v144, 0x18000, v142
	v_add_u32_e32 v148, 0x18400, v142
	v_add_u32_e32 v152, 0x18800, v142
	v_add_u32_e32 v156, 0x18c00, v142
	v_or_b32_e32 v160, 0x1c000, v142
	v_add_u32_e32 v164, 0x1c400, v142
	v_add_u32_e32 v172, 0x1c800, v142
	v_add_u32_e32 v176, 0x1cc00, v142
	ds_read_b128 v[144:147], v144
	ds_read_b128 v[148:151], v148
	ds_read_b128 v[152:155], v152
	ds_read_b128 v[156:159], v156
	ds_read_b128 v[160:163], v160
	ds_read_b128 v[164:167], v164
	ds_read_b128 v[172:175], v172
	ds_read_b128 v[176:179], v176
	s_add_u32 s42, s48, 0xa8000
	s_addc_u32 s43, s49, 0
	s_mov_b32 m0, s52
	ds_read_b128 v[180:183], v141 offset:32768
	ds_read_b128 v[184:187], v141 offset:33792
	ds_read_b128 v[188:191], v141 offset:34816
	ds_read_b128 v[192:195], v141 offset:35840
	ds_read_b128 v[208:211], v141 offset:36864
	ds_read_b128 v[212:215], v141 offset:37888
	ds_read_b128 v[216:219], v141 offset:38912
	ds_read_b128 v[220:223], v141 offset:39936
	global_load_lds_dwordx4 v134, s[42:43]
	v_lshl_add_u64 v[226:227], s[42:43], 0, v[132:133]
	s_mov_b32 m0, s53
	s_nop 0
	global_load_lds_dwordx4 v[226:227], off
	s_waitcnt vmcnt(8)
	s_waitcnt lgkmcnt(0)
	s_barrier
	s_setprio 1
	s_waitcnt lgkmcnt(0)
	v_mfma_f32_16x16x32_bf16 v[124:127], v[144:147], v[180:183], v[124:127]
	v_mfma_f32_16x16x32_bf16 v[120:123], v[152:155], v[180:183], v[120:123]
	v_mfma_f32_16x16x32_bf16 v[116:119], v[144:147], v[188:191], v[116:119]
	v_mfma_f32_16x16x32_bf16 v[112:115], v[152:155], v[188:191], v[112:115]
	v_mfma_f32_16x16x32_bf16 v[100:103], v[144:147], v[208:211], v[100:103]
	v_mfma_f32_16x16x32_bf16 v[96:99], v[152:155], v[208:211], v[96:99]
	v_mfma_f32_16x16x32_bf16 v[84:87], v[144:147], v[216:219], v[84:87]
	v_mfma_f32_16x16x32_bf16 v[80:83], v[152:155], v[216:219], v[80:83]
	v_mfma_f32_16x16x32_bf16 v[124:127], v[148:151], v[184:187], v[124:127]
	v_mfma_f32_16x16x32_bf16 v[120:123], v[156:159], v[184:187], v[120:123]
	v_mfma_f32_16x16x32_bf16 v[116:119], v[148:151], v[192:195], v[116:119]
	v_mfma_f32_16x16x32_bf16 v[112:115], v[156:159], v[192:195], v[112:115]
	v_mfma_f32_16x16x32_bf16 v[100:103], v[148:151], v[212:215], v[100:103]
	v_mfma_f32_16x16x32_bf16 v[96:99], v[156:159], v[212:215], v[96:99]
	v_mfma_f32_16x16x32_bf16 v[84:87], v[148:151], v[220:223], v[84:87]
	v_mfma_f32_16x16x32_bf16 v[80:83], v[156:159], v[220:223], v[80:83]
	s_setprio 0
	s_setprio 1
	v_mfma_f32_16x16x32_bf16 v[108:111], v[160:163], v[180:183], v[108:111]
	v_mfma_f32_16x16x32_bf16 v[104:107], v[172:175], v[180:183], v[104:107]
	v_mfma_f32_16x16x32_bf16 v[92:95], v[160:163], v[188:191], v[92:95]
	v_mfma_f32_16x16x32_bf16 v[88:91], v[172:175], v[188:191], v[88:91]
	v_mfma_f32_16x16x32_bf16 v[76:79], v[160:163], v[208:211], v[76:79]
	v_mfma_f32_16x16x32_bf16 v[72:75], v[172:175], v[208:211], v[72:75]
	v_mfma_f32_16x16x32_bf16 v[68:71], v[160:163], v[216:219], v[68:71]
	v_mfma_f32_16x16x32_bf16 v[64:67], v[172:175], v[216:219], v[64:67]
	v_mfma_f32_16x16x32_bf16 v[108:111], v[164:167], v[184:187], v[108:111]
	v_mfma_f32_16x16x32_bf16 v[104:107], v[176:179], v[184:187], v[104:107]
	v_mfma_f32_16x16x32_bf16 v[92:95], v[164:167], v[192:195], v[92:95]
	v_mfma_f32_16x16x32_bf16 v[88:91], v[176:179], v[192:195], v[88:91]
	v_mfma_f32_16x16x32_bf16 v[76:79], v[164:167], v[212:215], v[76:79]
	v_mfma_f32_16x16x32_bf16 v[72:75], v[176:179], v[212:215], v[72:75]
	v_mfma_f32_16x16x32_bf16 v[68:71], v[164:167], v[220:223], v[68:71]
	v_mfma_f32_16x16x32_bf16 v[64:67], v[176:179], v[220:223], v[64:67]
	s_setprio 0
	s_barrier
; #define PG8_STAGE(bufoff, gbase, voff) do { _Pragma("unroll") for (int _i = 0; _i < 2; ++_i) \
;         __builtin_amdgcn_global_load_lds((const unsigned*)((const char*)(gbase) + (voff)[_i]), (LAS unsigned*)(lds + (bufoff) + ldsw + _i * 8192), 16, 0, 0); } while (0)
; #define PG8_LDA(dst, b, h) do { _Pragma("unroll") for (int m = 0; m < 4; ++m) _Pragma("unroll") for (int k = 0; k < 2; ++k) dst[m][k] = *(const LAS bf16x8*)(lds + PG8_SA(b, h) + aoff + m * 2048 + k * 1024); } while (0)
; #define PG8_LDB(dst, b, h) do { _Pragma("unroll") for (int n = 0; n < 2; ++n) _Pragma("unroll") for (int k = 0; k < 2; ++k) dst[n][k] = *(const LAS bf16x8*)(lds + PG8_SB(b, h) + boff + n * 2048 + k * 1024); } while (0)
; #define PG8_MMA(ai, bj, At, Bt) do { __builtin_amdgcn_s_setprio(1); _Pragma("unroll") for (int m = 0; m < 4; ++m) _Pragma("unroll") for (int n = 0; n < 2; ++n) _Pragma("unroll") for (int k = 0; k < 2; ++k) \
;         acc[ai][bj][m][n] = __builtin_amdgcn_mfma_f32_16x16x32_bf16(Bt[n][k], At[m][k], acc[ai][bj][m][n], 0, 0, 0); __builtin_amdgcn_s_setprio(0); } while (0)
; #define PG8_WAIT_V(n) asm volatile("s_waitcnt vmcnt(" #n ")" ::: "memory")
; #define PG8_WAIT_L(n) asm volatile("s_waitcnt lgkmcnt(" #n ")" ::: "memory")
; #define PG8_BAR __builtin_amdgcn_s_barrier()
; #define PG8_SCHED __builtin_amdgcn_sched_barrier(0)
; template <class Epi, class Sched, bool ALIGN_EPI = false, bool SP2 = false>
; __device__ __forceinline__ void gemm_phase(LAS unsigned char* lds, const Gemm g, const Sched& S, const Epi& E) {
;     ...
;             PG8_LDB(B0, 1, 0); PG8_LDB(B1, 1, 1); PG8_SCHED; PG8_LDA(At, 1, 0); PG8_STAGE(PG8_SA(0, 1), a2 + hstep, voffA);
;             PG8_WAIT_V(8); PG8_WAIT_L(0); PG8_BAR; PG8_MMA(0, 0, At, B0); PG8_MMA(0, 1, At, B1); PG8_BAR; PG8_SCHED;
;             PG8_LDA(At, 1, 1); PG8_STAGE(PG8_SB(1, 0), b3, voffB); PG8_STAGE(PG8_SB(1, 1), b3 + hstep, voffB); PG8_STAGE(PG8_SA(1, 0), a3, voffA);
;             PG8_WAIT_V(8); PG8_WAIT_L(0); PG8_BAR; PG8_MMA(1, 0, At, B0); PG8_MMA(1, 1, At, B1); PG8_BAR; PG8_SCHED;
	s_mov_b32 m0, s56
	v_lshl_add_u64 v[168:169], v[168:169], 0, s[24:25]
	s_add_u32 s42, s46, 0xa8080
	ds_read_b128 v[180:183], v141 offset:49152
	ds_read_b128 v[184:187], v141 offset:50176
	ds_read_b128 v[188:191], v141 offset:51200
	ds_read_b128 v[192:195], v141 offset:52224
	ds_read_b128 v[208:211], v141 offset:53248
	ds_read_b128 v[212:215], v141 offset:54272
	ds_read_b128 v[216:219], v141 offset:55296
	ds_read_b128 v[220:223], v141 offset:56320
	global_load_lds_dwordx4 v[168:169], off
	v_lshl_add_u64 v[168:169], v[196:197], 0, s[24:25]
	s_mov_b32 m0, s57
	s_addc_u32 s43, s47, 0
	global_load_lds_dwordx4 v[168:169], off
	s_mov_b32 m0, s60
	s_nop 0
	s_nop 4
	global_load_lds_dwordx4 v128, s[42:43]
	v_lshl_add_u64 v[168:169], s[42:43], 0, v[130:131]
	s_mov_b32 m0, s61
	s_nop 0
	global_load_lds_dwordx4 v[168:169], off
	v_lshl_add_u64 v[168:169], v[200:201], 0, s[24:25]
	s_mov_b32 m0, s58
	s_nop 0
	global_load_lds_dwordx4 v[168:169], off
	v_lshl_add_u64 v[168:169], v[224:225], 0, s[24:25]
	s_mov_b32 m0, s59
	s_nop 0
	global_load_lds_dwordx4 v[168:169], off
	s_waitcnt vmcnt(8)
	s_waitcnt lgkmcnt(0)
	s_barrier
	s_setprio 1
	s_waitcnt lgkmcnt(0)
	v_mfma_f32_16x16x32_bf16 v[60:63], v[144:147], v[180:183], v[60:63]
	v_mfma_f32_16x16x32_bf16 v[56:59], v[152:155], v[180:183], v[56:59]
	v_mfma_f32_16x16x32_bf16 v[52:55], v[144:147], v[188:191], v[52:55]
	v_mfma_f32_16x16x32_bf16 v[48:51], v[152:155], v[188:191], v[48:51]
	v_mfma_f32_16x16x32_bf16 v[36:39], v[144:147], v[208:211], v[36:39]
	v_mfma_f32_16x16x32_bf16 v[32:35], v[152:155], v[208:211], v[32:35]
	v_mfma_f32_16x16x32_bf16 v[20:23], v[144:147], v[216:219], v[20:23]
	v_mfma_f32_16x16x32_bf16 v[16:19], v[152:155], v[216:219], v[16:19]
	v_mfma_f32_16x16x32_bf16 v[60:63], v[148:151], v[184:187], v[60:63]
	v_mfma_f32_16x16x32_bf16 v[56:59], v[156:159], v[184:187], v[56:59]
	v_mfma_f32_16x16x32_bf16 v[52:55], v[148:151], v[192:195], v[52:55]
	v_mfma_f32_16x16x32_bf16 v[48:51], v[156:159], v[192:195], v[48:51]
	v_mfma_f32_16x16x32_bf16 v[36:39], v[148:151], v[212:215], v[36:39]
	v_mfma_f32_16x16x32_bf16 v[32:35], v[156:159], v[212:215], v[32:35]
	v_mfma_f32_16x16x32_bf16 v[20:23], v[148:151], v[220:223], v[20:23]
	v_mfma_f32_16x16x32_bf16 v[16:19], v[156:159], v[220:223], v[16:19]
	s_setprio 0
	s_setprio 1
	v_mfma_f32_16x16x32_bf16 v[44:47], v[160:163], v[180:183], v[44:47]
	v_mfma_f32_16x16x32_bf16 v[40:43], v[172:175], v[180:183], v[40:43]
	v_mfma_f32_16x16x32_bf16 v[28:31], v[160:163], v[188:191], v[28:31]
	v_mfma_f32_16x16x32_bf16 v[24:27], v[172:175], v[188:191], v[24:27]
	v_mfma_f32_16x16x32_bf16 v[12:15], v[160:163], v[208:211], v[12:15]
	v_mfma_f32_16x16x32_bf16 v[8:11], v[172:175], v[208:211], v[8:11]
	v_mfma_f32_16x16x32_bf16 v[4:7], v[160:163], v[216:219], v[4:7]
	v_mfma_f32_16x16x32_bf16 v[0:3], v[172:175], v[216:219], v[0:3]
	v_mfma_f32_16x16x32_bf16 v[44:47], v[164:167], v[184:187], v[44:47]
	v_mfma_f32_16x16x32_bf16 v[40:43], v[176:179], v[184:187], v[40:43]
	v_mfma_f32_16x16x32_bf16 v[28:31], v[164:167], v[192:195], v[28:31]
	v_mfma_f32_16x16x32_bf16 v[24:27], v[176:179], v[192:195], v[24:27]
	v_mfma_f32_16x16x32_bf16 v[12:15], v[164:167], v[212:215], v[12:15]
	v_mfma_f32_16x16x32_bf16 v[8:11], v[176:179], v[212:215], v[8:11]
	v_mfma_f32_16x16x32_bf16 v[4:7], v[164:167], v[220:223], v[4:7]
	v_mfma_f32_16x16x32_bf16 v[0:3], v[176:179], v[220:223], v[0:3]
	s_setprio 0
	s_barrier
	s_add_i32 s71, s71, 2
	s_add_u32 s69, s69, 0x100
	s_addc_u32 s70, s70, 0
	s_cmp_gt_u32 s71, 39
	s_mov_b64 s[42:43], s[44:45]
	s_cbranch_scc0 .LBB0_41
; DI unsigned pack2(float lo, float hi) { f32x2 v = {lo, hi}; bf16x2_t b = __builtin_convertvector(v, bf16x2_t); return __builtin_bit_cast(unsigned, b); }
; #define PG8_WAIT_V(n) asm volatile("s_waitcnt vmcnt(" #n ")" ::: "memory")
; #define PG8_BAR __builtin_amdgcn_s_barrier()
; template <class Epi, class Sched, bool ALIGN_EPI = false, bool SP2 = false>
; __device__ __forceinline__ void gemm_phase(LAS unsigned char* lds, const Gemm g, const Sched& S, const Epi& E) {
;     ...
;         if (!has_next) break;
; #pragma unroll
;         for (int a = 0; a < 2; ++a)
; #pragma unroll
;             for (int b = 0; b < 2; ++b)
; #pragma unroll
;                 for (int m = 0; m < 4; ++m)
; #pragma unroll
;                     for (int n = 0; n < 2; ++n) acc[a][b][m][n] = (f32x4){0.f, 0.f, 0.f, 0.f};
;         cur = nxt; cA = nA; cB = nB; ++ui;
;         if constexpr (ALIGN_EPI) { if (wr == 1) PG8_BAR; }
;     }
;     PG8_WAIT_V(0);
;     if constexpr (!ALIGN_EPI) { if (wr == 0) PG8_BAR; }
;     DI void operator()(const f32x4 (&acc)[2][2][4][2], const Unit& u, int wr, int wc, int fr, int fq) const {
;         const int row0 = u.pm * BM + wr * 64 + fr, col0 = u.pn * BM + wc * 32 + 8 * fq;
; #pragma unroll
;         for (int ai = 0; ai < 2; ++ai)
; #pragma unroll
;             for (int m = 0; m < 4; ++m) {
;                 bf16_t* rowp = O + (size_t)(row0 + ai * HALF + m * 16) * D + col0;
; #pragma unroll
;                 for (int bj = 0; bj < 2; ++bj) {
;                     const f32x4 v0 = acc[ai][bj][m][0], v1 = acc[ai][bj][m][1];
;                     u32x4 w; w.x = pack2(v0[0], v0[1]); w.y = pack2(v0[2], v0[3]); w.z = pack2(v1[0], v1[1]); w.w = pack2(v1[2], v1[3]);
;                     *(u32x4*)(rowp + bj * HALF) = w;
;                 }
;             }
;     }
	v_lshl_add_u32 v144, s62, 8, v140
	v_lshl_or_b32 v146, s66, 8, v143
	v_ashrrev_i32_e32 v145, 31, v144
	v_ashrrev_i32_e32 v147, 31, v146
	v_lshlrev_b64 v[148:149], 11, v[144:145]
	v_lshl_add_u64 v[148:149], s[80:81], 0, v[148:149]
	v_lshlrev_b64 v[146:147], 1, v[146:147]
	v_lshl_add_u64 v[148:149], v[148:149], 0, v[146:147]
	s_mov_b64 s[42:43], 0x40000
	v_cvt_pk_bf16_f32 v68, v68, v69
	v_cvt_pk_bf16_f32 v69, v70, v71
	v_cvt_pk_bf16_f32 v70, v64, v65
	v_lshl_add_u64 v[64:65], v[148:149], 0, s[42:43]
	s_mov_b32 s42, 0x40000
	v_cvt_pk_bf16_f32 v60, v60, v61
	v_cvt_pk_bf16_f32 v61, v62, v63
	v_cvt_pk_bf16_f32 v62, v56, v57
	v_add_co_u32_e32 v56, vcc, s42, v148
	v_cvt_pk_bf16_f32 v44, v44, v45
	v_cvt_pk_bf16_f32 v45, v46, v47
	v_cvt_pk_bf16_f32 v46, v40, v41
	v_cvt_pk_bf16_f32 v47, v42, v43
	s_mov_b64 s[42:43], 0x48000
	v_addc_co_u32_e32 v57, vcc, 0, v149, vcc
	global_store_dwordx4 v[64:65], v[44:47], off offset:256
	v_cvt_pk_bf16_f32 v108, v108, v109
	v_cvt_pk_bf16_f32 v109, v110, v111
	v_lshl_add_u64 v[44:45], v[148:149], 0, s[42:43]
	s_mov_b32 s42, 0x48000
	v_cvt_pk_bf16_f32 v110, v104, v105
	v_or_b32_e32 v104, 16, v144
	v_add_co_u32_e32 v46, vcc, s42, v148
	v_cvt_pk_bf16_f32 v28, v28, v29
	v_cvt_pk_bf16_f32 v29, v30, v31
	v_cvt_pk_bf16_f32 v30, v24, v25
	v_cvt_pk_bf16_f32 v31, v26, v27
	s_mov_b64 s[42:43], 0x50000
	v_ashrrev_i32_e32 v105, 31, v104
	v_cvt_pk_bf16_f32 v92, v92, v93
	v_cvt_pk_bf16_f32 v93, v94, v95
	v_cvt_pk_bf16_f32 v94, v88, v89
	v_or_b32_e32 v88, 32, v144
	v_addc_co_u32_e32 v47, vcc, 0, v149, vcc
	global_store_dwordx4 v[44:45], v[28:31], off offset:256
	v_lshlrev_b64 v[104:105], 11, v[104:105]
	v_ashrrev_i32_e32 v89, 31, v88
	v_lshl_add_u64 v[28:29], v[148:149], 0, s[42:43]
	s_mov_b32 s42, 0x50000
	v_cvt_pk_bf16_f32 v76, v76, v77
	v_cvt_pk_bf16_f32 v77, v78, v79
	v_cvt_pk_bf16_f32 v78, v72, v73
	v_or_b32_e32 v72, 48, v144
	v_add_co_u32_e32 v30, vcc, s42, v148
	v_cvt_pk_bf16_f32 v12, v12, v13
	v_cvt_pk_bf16_f32 v13, v14, v15
	v_cvt_pk_bf16_f32 v14, v8, v9
	v_cvt_pk_bf16_f32 v15, v10, v11
	s_mov_b64 s[42:43], 0x58000
	v_cvt_pk_bf16_f32 v111, v106, v107
	v_lshl_add_u64 v[104:105], s[80:81], 0, v[104:105]
	v_lshlrev_b64 v[88:89], 11, v[88:89]
	v_ashrrev_i32_e32 v73, 31, v72
	v_addc_co_u32_e32 v31, vcc, 0, v149, vcc
	global_store_dwordx4 v[28:29], v[12:15], off offset:256
	global_store_dwordx4 v[148:149], v[108:111], off offset:256
	v_cvt_pk_bf16_f32 v95, v90, v91
	v_lshl_add_u64 v[12:13], v[148:149], 0, s[42:43]
	s_mov_b32 s42, 0x58000
	v_lshl_add_u64 v[108:109], v[104:105], 0, v[146:147]
	v_lshl_add_u64 v[88:89], s[80:81], 0, v[88:89]
	v_lshlrev_b64 v[72:73], 11, v[72:73]
	v_add_co_u32_e32 v14, vcc, s42, v148
	global_store_dwordx4 v[108:109], v[92:95], off offset:256
	v_cvt_pk_bf16_f32 v79, v74, v75
	v_lshl_add_u64 v[72:73], s[80:81], 0, v[72:73]
	v_lshl_add_u64 v[92:93], v[88:89], 0, v[146:147]
	v_addc_co_u32_e32 v15, vcc, 0, v149, vcc
	v_readlane_b32 s70, v254, 0
	v_cvt_pk_bf16_f32 v124, v124, v125
	v_cvt_pk_bf16_f32 v125, v126, v127
	v_cvt_pk_bf16_f32 v126, v120, v121
	v_cvt_pk_bf16_f32 v127, v122, v123
	v_cvt_pk_bf16_f32 v104, v116, v117
	v_cvt_pk_bf16_f32 v105, v118, v119
	v_cvt_pk_bf16_f32 v106, v112, v113
	v_cvt_pk_bf16_f32 v107, v114, v115
	v_cvt_pk_bf16_f32 v88, v100, v101
	v_cvt_pk_bf16_f32 v89, v102, v103
	v_cvt_pk_bf16_f32 v90, v96, v97
	v_cvt_pk_bf16_f32 v91, v98, v99
	global_store_dwordx4 v[92:93], v[76:79], off offset:256
	v_cvt_pk_bf16_f32 v74, v80, v81
	v_cvt_pk_bf16_f32 v75, v82, v83
	v_lshl_add_u64 v[76:77], v[72:73], 0, v[146:147]
	v_cvt_pk_bf16_f32 v72, v84, v85
	v_cvt_pk_bf16_f32 v73, v86, v87
	v_cvt_pk_bf16_f32 v71, v66, v67
	v_cvt_pk_bf16_f32 v63, v58, v59
	v_cvt_pk_bf16_f32 v40, v52, v53
	v_cvt_pk_bf16_f32 v41, v54, v55
	v_cvt_pk_bf16_f32 v42, v48, v49
	v_cvt_pk_bf16_f32 v43, v50, v51
	v_cvt_pk_bf16_f32 v24, v36, v37
	v_cvt_pk_bf16_f32 v25, v38, v39
	v_cvt_pk_bf16_f32 v26, v32, v33
	v_cvt_pk_bf16_f32 v27, v34, v35
	v_cvt_pk_bf16_f32 v8, v20, v21
	v_cvt_pk_bf16_f32 v9, v22, v23
	v_cvt_pk_bf16_f32 v10, v16, v17
	v_cvt_pk_bf16_f32 v11, v18, v19
	v_cvt_pk_bf16_f32 v4, v4, v5
	v_cvt_pk_bf16_f32 v5, v6, v7
	v_cvt_pk_bf16_f32 v6, v0, v1
	v_cvt_pk_bf16_f32 v7, v2, v3
	s_and_b64 vcc, exec, s[38:39]
	s_mov_b32 s66, s67
	s_mov_b32 s62, s68
	s_mov_b64 s[44:45], s[40:41]
	s_mov_b64 s[42:43], s[0:1]
	v_readlane_b32 s71, v254, 1
	global_store_dwordx4 v[148:149], v[124:127], off
	global_store_dwordx4 v[108:109], v[104:107], off
	global_store_dwordx4 v[92:93], v[88:91], off
	global_store_dwordx4 v[76:77], v[72:75], off
	global_store_dwordx4 v[76:77], v[68:71], off offset:256
	global_store_dwordx4 v[56:57], v[60:63], off
	global_store_dwordx4 v[46:47], v[40:43], off
	global_store_dwordx4 v[30:31], v[24:27], off
	global_store_dwordx4 v[14:15], v[8:11], off
	global_store_dwordx4 v[12:13], v[4:7], off offset:256
	s_cbranch_vccz .LBB0_34
	s_waitcnt vmcnt(0)
	s_cmpk_gt_u32 s2, 0xff
	s_cbranch_scc1 .LBB0_45
	s_barrier

; #define PG8_STAGE(bufoff, gbase, voff) do { _Pragma("unroll") for (int _i = 0; _i < 2; ++_i) \
;         __builtin_amdgcn_global_load_lds((const unsigned*)((const char*)(gbase) + (voff)[_i]), (LAS unsigned*)(lds + (bufoff) + ldsw + _i * 8192), 16, 0, 0); } while (0)
; #define PG8_LDA(dst, b, h) do { _Pragma("unroll") for (int m = 0; m < 4; ++m) _Pragma("unroll") for (int k = 0; k < 2; ++k) dst[m][k] = *(const LAS bf16x8*)(lds + PG8_SA(b, h) + aoff + m * 2048 + k * 1024); } while (0)
; #define PG8_LDB(dst, b, h) do { _Pragma("unroll") for (int n = 0; n < 2; ++n) _Pragma("unroll") for (int k = 0; k < 2; ++k) dst[n][k] = *(const LAS bf16x8*)(lds + PG8_SB(b, h) + boff + n * 2048 + k * 1024); } while (0)
; #define PG8_MMA(ai, bj, At, Bt) do { __builtin_amdgcn_s_setprio(1); _Pragma("unroll") for (int m = 0; m < 4; ++m) _Pragma("unroll") for (int n = 0; n < 2; ++n) _Pragma("unroll") for (int k = 0; k < 2; ++k) \
;         acc[ai][bj][m][n] = __builtin_amdgcn_mfma_f32_16x16x32_bf16(Bt[n][k], At[m][k], acc[ai][bj][m][n], 0, 0, 0); __builtin_amdgcn_s_setprio(0); } while (0)
; #define PG8_WAIT_V(n) asm volatile("s_waitcnt vmcnt(" #n ")" ::: "memory")
; #define PG8_WAIT_L(n) asm volatile("s_waitcnt lgkmcnt(" #n ")" ::: "memory")
; template <class Epi, class Sched, bool ALIGN_EPI = false, bool SP2 = false>
; __device__ __forceinline__ void gemm_phase(LAS unsigned char* lds, const Gemm g, const Sched& S, const Epi& E) {
;     ...
;         for (int t = 0; t < nt; t += 2) {
;             const bool last = (t == nt - 2);
;             const char* a1 = cA + (size_t)(t + 1) * kstep;
;             const char* a2 = last ? nA : cA + (size_t)(t + 2) * kstep; const char* b2 = last ? nB : cB + (size_t)(t + 2) * kstep;
;             const char* a3 = a2 + kstep; const char* b3 = b2 + kstep;
;             if (last && has_next) S.a_ready(nxt);
;             if constexpr (SP2) {
;             PG8_LDB(B0, 0, 0); PG8_LDB(B1, 0, 1); PG8_SCHED; PG8_LDA(At, 0, 0); PG8_STAGE(PG8_SA(1, 1), a1 + hstep, voffA);
;             PG8_WAIT_V(8); PG8_WAIT_L(0); PG8_BAR; PG8_MMA(0, 0, At, B0); PG8_MMA(0, 1, At, B1); PG8_BAR; PG8_SCHED;
;             PG8_LDA(At, 0, 1); PG8_STAGE(PG8_SB(0, 0), b2, voffB); PG8_STAGE(PG8_SB(0, 1), b2 + hstep, voffB); PG8_STAGE(PG8_SA(0, 0), a2, voffA);
;             PG8_WAIT_V(8); PG8_WAIT_L(0); PG8_BAR; PG8_MMA(1, 0, At, B0); PG8_MMA(1, 1, At, B1); PG8_BAR; PG8_SCHED;
.LBB0_69:
	v_or_b32_e32 v130, 0x10000, v175
	v_add_u32_e32 v134, 0x10400, v175
	v_add_u32_e32 v138, 0x10800, v175
	v_add_u32_e32 v142, 0x10c00, v175
	v_or_b32_e32 v146, 0x14000, v175
	v_add_u32_e32 v160, 0x14400, v175
	v_add_u32_e32 v164, 0x14800, v175
	ds_read_b128 v[130:133], v130
	ds_read_b128 v[134:137], v134
	ds_read_b128 v[138:141], v138
	ds_read_b128 v[142:145], v142
	ds_read_b128 v[146:149], v146
	ds_read_b128 v[160:163], v160
	v_add_u32_e32 v168, 0x14c00, v175
	ds_read_b128 v[164:167], v164
	ds_read_b128 v[176:179], v168
	s_add_u32 s40, s0, 0xfffc0080
	s_addc_u32 s41, s1, -1
	s_cmp_eq_u32 s47, 12
	s_cselect_b32 s45, s67, s41
	s_cselect_b32 s44, s66, s40
	s_cselect_b32 s41, s38, s46
	s_cselect_b32 s40, s39, s43
	s_add_i32 m0, s60, 0xc000
	ds_read_b128 v[180:183], v174
	ds_read_b128 v[184:187], v174 offset:1024
	ds_read_b128 v[188:191], v174 offset:2048
	ds_read_b128 v[192:195], v174 offset:3072
	ds_read_b128 v[208:211], v174 offset:4096
	ds_read_b128 v[212:215], v174 offset:5120
	ds_read_b128 v[216:219], v174 offset:6144
	ds_read_b128 v[220:223], v174 offset:7168
	global_load_lds_dwordx4 v156, s[0:1]
	s_add_i32 m0, s60, 0xe000
	s_nop 0
	global_load_lds_dwordx4 v158, s[0:1]
	s_waitcnt vmcnt(8)
	s_waitcnt lgkmcnt(0)
	s_barrier
	s_setprio 1
	s_waitcnt lgkmcnt(0)
	v_mfma_f32_16x16x32_bf16 v[124:127], v[130:133], v[180:183], v[124:127]
	v_mfma_f32_16x16x32_bf16 v[88:91], v[138:141], v[180:183], v[88:91]
	v_mfma_f32_16x16x32_bf16 v[120:123], v[130:133], v[188:191], v[120:123]
	v_mfma_f32_16x16x32_bf16 v[92:95], v[138:141], v[188:191], v[92:95]
	v_mfma_f32_16x16x32_bf16 v[116:119], v[130:133], v[208:211], v[116:119]
	v_mfma_f32_16x16x32_bf16 v[84:87], v[138:141], v[208:211], v[84:87]
	v_mfma_f32_16x16x32_bf16 v[112:115], v[130:133], v[216:219], v[112:115]
	v_mfma_f32_16x16x32_bf16 v[80:83], v[138:141], v[216:219], v[80:83]
	v_mfma_f32_16x16x32_bf16 v[124:127], v[134:137], v[184:187], v[124:127]
	v_mfma_f32_16x16x32_bf16 v[88:91], v[142:145], v[184:187], v[88:91]
	v_mfma_f32_16x16x32_bf16 v[120:123], v[134:137], v[192:195], v[120:123]
	v_mfma_f32_16x16x32_bf16 v[92:95], v[142:145], v[192:195], v[92:95]
	v_mfma_f32_16x16x32_bf16 v[116:119], v[134:137], v[212:215], v[116:119]
	v_mfma_f32_16x16x32_bf16 v[84:87], v[142:145], v[212:215], v[84:87]
	v_mfma_f32_16x16x32_bf16 v[112:115], v[134:137], v[220:223], v[112:115]
	v_mfma_f32_16x16x32_bf16 v[80:83], v[142:145], v[220:223], v[80:83]
	s_setprio 0
	s_setprio 1
	v_mfma_f32_16x16x32_bf16 v[104:107], v[146:149], v[180:183], v[104:107]
	v_mfma_f32_16x16x32_bf16 v[72:75], v[164:167], v[180:183], v[72:75]
	v_mfma_f32_16x16x32_bf16 v[108:111], v[146:149], v[188:191], v[108:111]
	v_mfma_f32_16x16x32_bf16 v[76:79], v[164:167], v[188:191], v[76:79]
	v_mfma_f32_16x16x32_bf16 v[100:103], v[146:149], v[208:211], v[100:103]
	v_mfma_f32_16x16x32_bf16 v[68:71], v[164:167], v[208:211], v[68:71]
	v_mfma_f32_16x16x32_bf16 v[96:99], v[146:149], v[216:219], v[96:99]
	v_mfma_f32_16x16x32_bf16 v[64:67], v[164:167], v[216:219], v[64:67]
	v_mfma_f32_16x16x32_bf16 v[104:107], v[160:163], v[184:187], v[104:107]
	v_mfma_f32_16x16x32_bf16 v[72:75], v[176:179], v[184:187], v[72:75]
	v_mfma_f32_16x16x32_bf16 v[108:111], v[160:163], v[192:195], v[108:111]
	v_mfma_f32_16x16x32_bf16 v[76:79], v[176:179], v[192:195], v[76:79]
	v_mfma_f32_16x16x32_bf16 v[100:103], v[160:163], v[212:215], v[100:103]
	v_mfma_f32_16x16x32_bf16 v[68:71], v[176:179], v[212:215], v[68:71]
	v_mfma_f32_16x16x32_bf16 v[96:99], v[160:163], v[220:223], v[96:99]
	v_mfma_f32_16x16x32_bf16 v[64:67], v[176:179], v[220:223], v[64:67]
	s_setprio 0
	s_barrier
	s_mov_b32 m0, s62
	v_lshl_add_u64 v[168:169], s[40:41], 0, v[150:151]
	s_add_u32 s48, s40, 0x40000
	ds_read_b128 v[180:183], v174 offset:16384
	ds_read_b128 v[184:187], v174 offset:17408
	ds_read_b128 v[188:191], v174 offset:18432
	ds_read_b128 v[192:195], v174 offset:19456
	ds_read_b128 v[208:211], v174 offset:20480
	ds_read_b128 v[212:215], v174 offset:21504
	ds_read_b128 v[216:219], v174 offset:22528
	ds_read_b128 v[220:223], v174 offset:23552
	global_load_lds_dwordx4 v[168:169], off
	v_lshl_add_u64 v[196:197], s[40:41], 0, v[154:155]
	s_mov_b32 m0, s63
	s_addc_u32 s49, s41, 0
	global_load_lds_dwordx4 v[196:197], off
	s_mov_b32 m0, s22
	v_lshl_add_u64 v[224:225], s[44:45], 0, v[152:153]
	s_nop 4
	global_load_lds_dwordx4 v150, s[48:49]
	s_mov_b32 m0, s23
	s_nop 0
	global_load_lds_dwordx4 v154, s[48:49]
	v_lshl_add_u64 v[200:201], s[44:45], 0, v[128:129]
	s_mov_b32 m0, s60
	s_nop 0
	global_load_lds_dwordx4 v[200:201], off
	s_mov_b32 m0, s30
	s_nop 0
	global_load_lds_dwordx4 v[224:225], off
	s_waitcnt vmcnt(8)
	s_waitcnt lgkmcnt(0)
	s_barrier
; #define PG8_STAGE(bufoff, gbase, voff) do { _Pragma("unroll") for (int _i = 0; _i < 2; ++_i) \
;         __builtin_amdgcn_global_load_lds((const unsigned*)((const char*)(gbase) + (voff)[_i]), (LAS unsigned*)(lds + (bufoff) + ldsw + _i * 8192), 16, 0, 0); } while (0)
; #define PG8_LDA(dst, b, h) do { _Pragma("unroll") for (int m = 0; m < 4; ++m) _Pragma("unroll") for (int k = 0; k < 2; ++k) dst[m][k] = *(const LAS bf16x8*)(lds + PG8_SA(b, h) + aoff + m * 2048 + k * 1024); } while (0)
; #define PG8_LDB(dst, b, h) do { _Pragma("unroll") for (int n = 0; n < 2; ++n) _Pragma("unroll") for (int k = 0; k < 2; ++k) dst[n][k] = *(const LAS bf16x8*)(lds + PG8_SB(b, h) + boff + n * 2048 + k * 1024); } while (0)
; #define PG8_MMA(ai, bj, At, Bt) do { __builtin_amdgcn_s_setprio(1); _Pragma("unroll") for (int m = 0; m < 4; ++m) _Pragma("unroll") for (int n = 0; n < 2; ++n) _Pragma("unroll") for (int k = 0; k < 2; ++k) \
;         acc[ai][bj][m][n] = __builtin_amdgcn_mfma_f32_16x16x32_bf16(Bt[n][k], At[m][k], acc[ai][bj][m][n], 0, 0, 0); __builtin_amdgcn_s_setprio(0); } while (0)
; #define PG8_WAIT_V(n) asm volatile("s_waitcnt vmcnt(" #n ")" ::: "memory")
; #define PG8_WAIT_L(n) asm volatile("s_waitcnt lgkmcnt(" #n ")" ::: "memory")
; #define PG8_BAR __builtin_amdgcn_s_barrier()
; #define PG8_SCHED __builtin_amdgcn_sched_barrier(0)
; template <class Epi, class Sched, bool ALIGN_EPI = false, bool SP2 = false>
; __device__ __forceinline__ void gemm_phase(LAS unsigned char* lds, const Gemm g, const Sched& S, const Epi& E) {
;     ...
;             PG8_LDA(At, 0, 1); PG8_STAGE(PG8_SB(0, 0), b2, voffB); PG8_STAGE(PG8_SB(0, 1), b2 + hstep, voffB); PG8_STAGE(PG8_SA(0, 0), a2, voffA);
;             PG8_WAIT_V(8); PG8_WAIT_L(0); PG8_BAR; PG8_MMA(1, 0, At, B0); PG8_MMA(1, 1, At, B1); PG8_BAR; PG8_SCHED;
;             PG8_LDB(B0, 1, 0); PG8_LDB(B1, 1, 1); PG8_SCHED; PG8_LDA(At, 1, 0); PG8_STAGE(PG8_SA(0, 1), a2 + hstep, voffA);
;             PG8_WAIT_V(8); PG8_WAIT_L(0); PG8_BAR; PG8_MMA(0, 0, At, B0); PG8_MMA(0, 1, At, B1); PG8_BAR; PG8_SCHED;
;             PG8_LDA(At, 1, 1); PG8_STAGE(PG8_SB(1, 0), b3, voffB); PG8_STAGE(PG8_SB(1, 1), b3 + hstep, voffB); PG8_STAGE(PG8_SA(1, 0), a3, voffA);
	s_setprio 1
	s_waitcnt lgkmcnt(0)
	v_mfma_f32_16x16x32_bf16 v[60:63], v[130:133], v[180:183], v[60:63]
	v_mfma_f32_16x16x32_bf16 v[28:31], v[138:141], v[180:183], v[28:31]
	v_mfma_f32_16x16x32_bf16 v[56:59], v[130:133], v[188:191], v[56:59]
	v_mfma_f32_16x16x32_bf16 v[24:27], v[138:141], v[188:191], v[24:27]
	v_mfma_f32_16x16x32_bf16 v[52:55], v[130:133], v[208:211], v[52:55]
	v_mfma_f32_16x16x32_bf16 v[20:23], v[138:141], v[208:211], v[20:23]
	v_mfma_f32_16x16x32_bf16 v[48:51], v[130:133], v[216:219], v[48:51]
	v_mfma_f32_16x16x32_bf16 v[16:19], v[138:141], v[216:219], v[16:19]
	v_mfma_f32_16x16x32_bf16 v[60:63], v[134:137], v[184:187], v[60:63]
	v_mfma_f32_16x16x32_bf16 v[28:31], v[142:145], v[184:187], v[28:31]
	v_mfma_f32_16x16x32_bf16 v[56:59], v[134:137], v[192:195], v[56:59]
	v_mfma_f32_16x16x32_bf16 v[24:27], v[142:145], v[192:195], v[24:27]
	v_mfma_f32_16x16x32_bf16 v[52:55], v[134:137], v[212:215], v[52:55]
	v_mfma_f32_16x16x32_bf16 v[20:23], v[142:145], v[212:215], v[20:23]
	v_mfma_f32_16x16x32_bf16 v[48:51], v[134:137], v[220:223], v[48:51]
	v_mfma_f32_16x16x32_bf16 v[16:19], v[142:145], v[220:223], v[16:19]
	s_setprio 0
	s_setprio 1
	v_mfma_f32_16x16x32_bf16 v[44:47], v[146:149], v[180:183], v[44:47]
	v_mfma_f32_16x16x32_bf16 v[12:15], v[164:167], v[180:183], v[12:15]
	v_mfma_f32_16x16x32_bf16 v[40:43], v[146:149], v[188:191], v[40:43]
	v_mfma_f32_16x16x32_bf16 v[8:11], v[164:167], v[188:191], v[8:11]
	v_mfma_f32_16x16x32_bf16 v[36:39], v[146:149], v[208:211], v[36:39]
	v_mfma_f32_16x16x32_bf16 v[4:7], v[164:167], v[208:211], v[4:7]
	v_mfma_f32_16x16x32_bf16 v[32:35], v[146:149], v[216:219], v[32:35]
	v_mfma_f32_16x16x32_bf16 v[0:3], v[164:167], v[216:219], v[0:3]
	v_mfma_f32_16x16x32_bf16 v[44:47], v[160:163], v[184:187], v[44:47]
	v_mfma_f32_16x16x32_bf16 v[12:15], v[176:179], v[184:187], v[12:15]
	v_mfma_f32_16x16x32_bf16 v[40:43], v[160:163], v[192:195], v[40:43]
	v_mfma_f32_16x16x32_bf16 v[8:11], v[176:179], v[192:195], v[8:11]
	v_mfma_f32_16x16x32_bf16 v[36:39], v[160:163], v[212:215], v[36:39]
	v_mfma_f32_16x16x32_bf16 v[4:7], v[176:179], v[212:215], v[4:7]
	v_mfma_f32_16x16x32_bf16 v[32:35], v[160:163], v[220:223], v[32:35]
	v_mfma_f32_16x16x32_bf16 v[0:3], v[176:179], v[220:223], v[0:3]
	s_setprio 0
	s_barrier
	v_or_b32_e32 v130, 0x18000, v175
	v_add_u32_e32 v134, 0x18400, v175
	v_add_u32_e32 v138, 0x18800, v175
	v_add_u32_e32 v142, 0x18c00, v175
	v_or_b32_e32 v146, 0x1c000, v175
	v_add_u32_e32 v160, 0x1c400, v175
	v_add_u32_e32 v164, 0x1c800, v175
	v_add_u32_e32 v176, 0x1cc00, v175
	ds_read_b128 v[130:133], v130
	ds_read_b128 v[134:137], v134
	ds_read_b128 v[138:141], v138
	ds_read_b128 v[142:145], v142
	ds_read_b128 v[146:149], v146
	ds_read_b128 v[160:163], v160
	ds_read_b128 v[164:167], v164
	ds_read_b128 v[176:179], v176
	s_add_u32 s44, s44, 0x40000
	s_addc_u32 s45, s45, 0
	s_mov_b32 m0, s31
	ds_read_b128 v[180:183], v174 offset:32768
	ds_read_b128 v[184:187], v174 offset:33792
	ds_read_b128 v[188:191], v174 offset:34816
	ds_read_b128 v[192:195], v174 offset:35840
	ds_read_b128 v[208:211], v174 offset:36864
	ds_read_b128 v[212:215], v174 offset:37888
	ds_read_b128 v[216:219], v174 offset:38912
	ds_read_b128 v[220:223], v174 offset:39936
	global_load_lds_dwordx4 v128, s[44:45]
	v_lshl_add_u64 v[226:227], s[44:45], 0, v[152:153]
	s_mov_b32 m0, s36
	s_nop 0
	global_load_lds_dwordx4 v[226:227], off
	s_waitcnt vmcnt(8)
	s_waitcnt lgkmcnt(0)
	s_barrier
	s_setprio 1
	s_waitcnt lgkmcnt(0)
	v_mfma_f32_16x16x32_bf16 v[124:127], v[130:133], v[180:183], v[124:127]
	v_mfma_f32_16x16x32_bf16 v[88:91], v[138:141], v[180:183], v[88:91]
	v_mfma_f32_16x16x32_bf16 v[120:123], v[130:133], v[188:191], v[120:123]
	v_mfma_f32_16x16x32_bf16 v[92:95], v[138:141], v[188:191], v[92:95]
	v_mfma_f32_16x16x32_bf16 v[116:119], v[130:133], v[208:211], v[116:119]
	v_mfma_f32_16x16x32_bf16 v[84:87], v[138:141], v[208:211], v[84:87]
	v_mfma_f32_16x16x32_bf16 v[112:115], v[130:133], v[216:219], v[112:115]
	v_mfma_f32_16x16x32_bf16 v[80:83], v[138:141], v[216:219], v[80:83]
	v_mfma_f32_16x16x32_bf16 v[124:127], v[134:137], v[184:187], v[124:127]
	v_mfma_f32_16x16x32_bf16 v[88:91], v[142:145], v[184:187], v[88:91]
	v_mfma_f32_16x16x32_bf16 v[120:123], v[134:137], v[192:195], v[120:123]
	v_mfma_f32_16x16x32_bf16 v[92:95], v[142:145], v[192:195], v[92:95]
	v_mfma_f32_16x16x32_bf16 v[116:119], v[134:137], v[212:215], v[116:119]
	v_mfma_f32_16x16x32_bf16 v[84:87], v[142:145], v[212:215], v[84:87]
	v_mfma_f32_16x16x32_bf16 v[112:115], v[134:137], v[220:223], v[112:115]
	v_mfma_f32_16x16x32_bf16 v[80:83], v[142:145], v[220:223], v[80:83]
	s_setprio 0
	s_setprio 1
	v_mfma_f32_16x16x32_bf16 v[104:107], v[146:149], v[180:183], v[104:107]
	v_mfma_f32_16x16x32_bf16 v[72:75], v[164:167], v[180:183], v[72:75]
	v_mfma_f32_16x16x32_bf16 v[108:111], v[146:149], v[188:191], v[108:111]
	v_mfma_f32_16x16x32_bf16 v[76:79], v[164:167], v[188:191], v[76:79]
	v_mfma_f32_16x16x32_bf16 v[100:103], v[146:149], v[208:211], v[100:103]
	v_mfma_f32_16x16x32_bf16 v[68:71], v[164:167], v[208:211], v[68:71]
	v_mfma_f32_16x16x32_bf16 v[96:99], v[146:149], v[216:219], v[96:99]
	v_mfma_f32_16x16x32_bf16 v[64:67], v[164:167], v[216:219], v[64:67]
	v_mfma_f32_16x16x32_bf16 v[104:107], v[160:163], v[184:187], v[104:107]
	v_mfma_f32_16x16x32_bf16 v[72:75], v[176:179], v[184:187], v[72:75]
	v_mfma_f32_16x16x32_bf16 v[108:111], v[160:163], v[192:195], v[108:111]
	v_mfma_f32_16x16x32_bf16 v[76:79], v[176:179], v[192:195], v[76:79]
	v_mfma_f32_16x16x32_bf16 v[100:103], v[160:163], v[212:215], v[100:103]
	v_mfma_f32_16x16x32_bf16 v[68:71], v[176:179], v[212:215], v[68:71]
	v_mfma_f32_16x16x32_bf16 v[96:99], v[160:163], v[220:223], v[96:99]
	v_mfma_f32_16x16x32_bf16 v[64:67], v[176:179], v[220:223], v[64:67]
	s_setprio 0
	s_barrier
; #define PG8_STAGE(bufoff, gbase, voff) do { _Pragma("unroll") for (int _i = 0; _i < 2; ++_i) \
;         __builtin_amdgcn_global_load_lds((const unsigned*)((const char*)(gbase) + (voff)[_i]), (LAS unsigned*)(lds + (bufoff) + ldsw + _i * 8192), 16, 0, 0); } while (0)
; #define PG8_LDA(dst, b, h) do { _Pragma("unroll") for (int m = 0; m < 4; ++m) _Pragma("unroll") for (int k = 0; k < 2; ++k) dst[m][k] = *(const LAS bf16x8*)(lds + PG8_SA(b, h) + aoff + m * 2048 + k * 1024); } while (0)
; #define PG8_LDB(dst, b, h) do { _Pragma("unroll") for (int n = 0; n < 2; ++n) _Pragma("unroll") for (int k = 0; k < 2; ++k) dst[n][k] = *(const LAS bf16x8*)(lds + PG8_SB(b, h) + boff + n * 2048 + k * 1024); } while (0)
; #define PG8_MMA(ai, bj, At, Bt) do { __builtin_amdgcn_s_setprio(1); _Pragma("unroll") for (int m = 0; m < 4; ++m) _Pragma("unroll") for (int n = 0; n < 2; ++n) _Pragma("unroll") for (int k = 0; k < 2; ++k) \
;         acc[ai][bj][m][n] = __builtin_amdgcn_mfma_f32_16x16x32_bf16(Bt[n][k], At[m][k], acc[ai][bj][m][n], 0, 0, 0); __builtin_amdgcn_s_setprio(0); } while (0)
; #define PG8_WAIT_V(n) asm volatile("s_waitcnt vmcnt(" #n ")" ::: "memory")
; #define PG8_WAIT_L(n) asm volatile("s_waitcnt lgkmcnt(" #n ")" ::: "memory")
; #define PG8_BAR __builtin_amdgcn_s_barrier()
; #define PG8_SCHED __builtin_amdgcn_sched_barrier(0)
; template <class Epi, class Sched, bool ALIGN_EPI = false, bool SP2 = false>
; __device__ __forceinline__ void gemm_phase(LAS unsigned char* lds, const Gemm g, const Sched& S, const Epi& E) {
;     ...
;             PG8_LDB(B0, 1, 0); PG8_LDB(B1, 1, 1); PG8_SCHED; PG8_LDA(At, 1, 0); PG8_STAGE(PG8_SA(0, 1), a2 + hstep, voffA);
;             PG8_WAIT_V(8); PG8_WAIT_L(0); PG8_BAR; PG8_MMA(0, 0, At, B0); PG8_MMA(0, 1, At, B1); PG8_BAR; PG8_SCHED;
;             PG8_LDA(At, 1, 1); PG8_STAGE(PG8_SB(1, 0), b3, voffB); PG8_STAGE(PG8_SB(1, 1), b3 + hstep, voffB); PG8_STAGE(PG8_SA(1, 0), a3, voffA);
;             PG8_WAIT_V(8); PG8_WAIT_L(0); PG8_BAR; PG8_MMA(1, 0, At, B0); PG8_MMA(1, 1, At, B1); PG8_BAR; PG8_SCHED;
;     ...
;         if constexpr (ALIGN_EPI) { if (wr == 0) PG8_BAR; }
	s_mov_b32 m0, s97
	v_lshl_add_u64 v[168:169], v[168:169], 0, s[24:25]
	s_add_u32 s40, s40, 0x40080
	ds_read_b128 v[180:183], v174 offset:49152
	ds_read_b128 v[184:187], v174 offset:50176
	ds_read_b128 v[188:191], v174 offset:51200
	ds_read_b128 v[192:195], v174 offset:52224
	ds_read_b128 v[208:211], v174 offset:53248
	ds_read_b128 v[212:215], v174 offset:54272
	ds_read_b128 v[216:219], v174 offset:55296
	ds_read_b128 v[220:223], v174 offset:56320
	global_load_lds_dwordx4 v[168:169], off
	v_lshl_add_u64 v[168:169], v[196:197], 0, s[24:25]
	s_mov_b32 m0, s70
	s_addc_u32 s41, s41, 0
	global_load_lds_dwordx4 v[168:169], off
	s_mov_b32 m0, s2
	s_nop 0
	s_nop 4
	global_load_lds_dwordx4 v150, s[40:41]
	v_lshl_add_u64 v[168:169], s[40:41], 0, v[154:155]
	s_mov_b32 m0, s26
	s_nop 0
	global_load_lds_dwordx4 v[168:169], off
	v_lshl_add_u64 v[168:169], v[200:201], 0, s[24:25]
	s_mov_b32 m0, s71
	s_nop 0
	global_load_lds_dwordx4 v[168:169], off
	v_lshl_add_u64 v[168:169], v[224:225], 0, s[24:25]
	s_mov_b32 m0, s99
	s_nop 0
	global_load_lds_dwordx4 v[168:169], off
	s_waitcnt vmcnt(8)
	s_waitcnt lgkmcnt(0)
	s_barrier
	s_setprio 1
	s_waitcnt lgkmcnt(0)
	v_mfma_f32_16x16x32_bf16 v[60:63], v[130:133], v[180:183], v[60:63]
	v_mfma_f32_16x16x32_bf16 v[28:31], v[138:141], v[180:183], v[28:31]
	v_mfma_f32_16x16x32_bf16 v[56:59], v[130:133], v[188:191], v[56:59]
	v_mfma_f32_16x16x32_bf16 v[24:27], v[138:141], v[188:191], v[24:27]
	v_mfma_f32_16x16x32_bf16 v[52:55], v[130:133], v[208:211], v[52:55]
	v_mfma_f32_16x16x32_bf16 v[20:23], v[138:141], v[208:211], v[20:23]
	v_mfma_f32_16x16x32_bf16 v[48:51], v[130:133], v[216:219], v[48:51]
	v_mfma_f32_16x16x32_bf16 v[16:19], v[138:141], v[216:219], v[16:19]
	v_mfma_f32_16x16x32_bf16 v[60:63], v[134:137], v[184:187], v[60:63]
	v_mfma_f32_16x16x32_bf16 v[28:31], v[142:145], v[184:187], v[28:31]
	v_mfma_f32_16x16x32_bf16 v[56:59], v[134:137], v[192:195], v[56:59]
	v_mfma_f32_16x16x32_bf16 v[24:27], v[142:145], v[192:195], v[24:27]
	v_mfma_f32_16x16x32_bf16 v[52:55], v[134:137], v[212:215], v[52:55]
	v_mfma_f32_16x16x32_bf16 v[20:23], v[142:145], v[212:215], v[20:23]
	v_mfma_f32_16x16x32_bf16 v[48:51], v[134:137], v[220:223], v[48:51]
	v_mfma_f32_16x16x32_bf16 v[16:19], v[142:145], v[220:223], v[16:19]
	s_setprio 0
	s_setprio 1
	v_mfma_f32_16x16x32_bf16 v[44:47], v[146:149], v[180:183], v[44:47]
	v_mfma_f32_16x16x32_bf16 v[12:15], v[164:167], v[180:183], v[12:15]
	v_mfma_f32_16x16x32_bf16 v[40:43], v[146:149], v[188:191], v[40:43]
	v_mfma_f32_16x16x32_bf16 v[8:11], v[164:167], v[188:191], v[8:11]
	v_mfma_f32_16x16x32_bf16 v[36:39], v[146:149], v[208:211], v[36:39]
	v_mfma_f32_16x16x32_bf16 v[4:7], v[164:167], v[208:211], v[4:7]
	v_mfma_f32_16x16x32_bf16 v[32:35], v[146:149], v[216:219], v[32:35]
	v_mfma_f32_16x16x32_bf16 v[0:3], v[164:167], v[216:219], v[0:3]
	v_mfma_f32_16x16x32_bf16 v[44:47], v[160:163], v[184:187], v[44:47]
	v_mfma_f32_16x16x32_bf16 v[12:15], v[176:179], v[184:187], v[12:15]
	v_mfma_f32_16x16x32_bf16 v[40:43], v[160:163], v[192:195], v[40:43]
	v_mfma_f32_16x16x32_bf16 v[8:11], v[176:179], v[192:195], v[8:11]
	v_mfma_f32_16x16x32_bf16 v[36:39], v[160:163], v[212:215], v[36:39]
	v_mfma_f32_16x16x32_bf16 v[4:7], v[176:179], v[212:215], v[4:7]
	v_mfma_f32_16x16x32_bf16 v[32:35], v[160:163], v[220:223], v[32:35]
	v_mfma_f32_16x16x32_bf16 v[0:3], v[176:179], v[220:223], v[0:3]
	s_setprio 0
	s_barrier
	s_add_i32 s47, s47, 2
	s_add_u32 s0, s0, 0x100
	s_addc_u32 s1, s1, 0
	s_add_u32 s43, s43, 0x100
	s_addc_u32 s46, s46, 0
	s_cmp_gt_u32 s47, 13
	s_cbranch_scc0 .LBB0_69
	v_readlane_b32 s0, v255, 2
	v_readlane_b32 s1, v255, 3
	s_and_b64 vcc, exec, s[0:1]
	s_cbranch_vccz .LBB0_72
	s_barrier

; #define PG8_STAGE(bufoff, gbase, voff) do { _Pragma("unroll") for (int _i = 0; _i < 2; ++_i) \
;         __builtin_amdgcn_global_load_lds((const unsigned*)((const char*)(gbase) + (voff)[_i]), (LAS unsigned*)(lds + (bufoff) + ldsw + _i * 8192), 16, 0, 0); } while (0)
; #define PG8_LDA(dst, b, h) do { _Pragma("unroll") for (int m = 0; m < 4; ++m) _Pragma("unroll") for (int k = 0; k < 2; ++k) dst[m][k] = *(const LAS bf16x8*)(lds + PG8_SA(b, h) + aoff + m * 2048 + k * 1024); } while (0)
; #define PG8_LDB(dst, b, h) do { _Pragma("unroll") for (int n = 0; n < 2; ++n) _Pragma("unroll") for (int k = 0; k < 2; ++k) dst[n][k] = *(const LAS bf16x8*)(lds + PG8_SB(b, h) + boff + n * 2048 + k * 1024); } while (0)
; #define PG8_MMA(ai, bj, At, Bt) do { __builtin_amdgcn_s_setprio(1); _Pragma("unroll") for (int m = 0; m < 4; ++m) _Pragma("unroll") for (int n = 0; n < 2; ++n) _Pragma("unroll") for (int k = 0; k < 2; ++k) \
;         acc[ai][bj][m][n] = __builtin_amdgcn_mfma_f32_16x16x32_bf16(Bt[n][k], At[m][k], acc[ai][bj][m][n], 0, 0, 0); __builtin_amdgcn_s_setprio(0); } while (0)
; #define PG8_WAIT_V(n) asm volatile("s_waitcnt vmcnt(" #n ")" ::: "memory")
; #define PG8_WAIT_L(n) asm volatile("s_waitcnt lgkmcnt(" #n ")" ::: "memory")
; template <class Epi, class Sched, bool ALIGN_EPI = false, bool SP2 = false>
; __device__ __forceinline__ void gemm_phase(LAS unsigned char* lds, const Gemm g, const Sched& S, const Epi& E) {
;     ...
;         for (int t = 0; t < nt; t += 2) {
;             const bool last = (t == nt - 2);
;             const char* a1 = cA + (size_t)(t + 1) * kstep;
;             const char* a2 = last ? nA : cA + (size_t)(t + 2) * kstep; const char* b2 = last ? nB : cB + (size_t)(t + 2) * kstep;
;             const char* a3 = a2 + kstep; const char* b3 = b2 + kstep;
;             if (last && has_next) S.a_ready(nxt);
;             if constexpr (SP2) {
;             PG8_LDB(B0, 0, 0); PG8_LDB(B1, 0, 1); PG8_SCHED; PG8_LDA(At, 0, 0); PG8_STAGE(PG8_SA(1, 1), a1 + hstep, voffA);
;             PG8_WAIT_V(8); PG8_WAIT_L(0); PG8_BAR; PG8_MMA(0, 0, At, B0); PG8_MMA(0, 1, At, B1); PG8_BAR; PG8_SCHED;
;             PG8_LDA(At, 0, 1); PG8_STAGE(PG8_SB(0, 0), b2, voffB); PG8_STAGE(PG8_SB(0, 1), b2 + hstep, voffB); PG8_STAGE(PG8_SA(0, 0), a2, voffA);
;             PG8_WAIT_V(8); PG8_WAIT_L(0); PG8_BAR; PG8_MMA(1, 0, At, B0); PG8_MMA(1, 1, At, B1); PG8_BAR; PG8_SCHED;
.LBB0_153:
	v_or_b32_e32 v144, 0x10000, v142
	v_add_u32_e32 v148, 0x10400, v142
	v_add_u32_e32 v152, 0x10800, v142
	v_add_u32_e32 v156, 0x10c00, v142
	v_or_b32_e32 v160, 0x14000, v142
	v_add_u32_e32 v164, 0x14400, v142
	v_add_u32_e32 v168, 0x14800, v142
	ds_read_b128 v[144:147], v144
	ds_read_b128 v[148:151], v148
	ds_read_b128 v[152:155], v152
	ds_read_b128 v[156:159], v156
	ds_read_b128 v[160:163], v160
	ds_read_b128 v[164:167], v164
	v_add_u32_e32 v169, 0x14c00, v142
	ds_read_b128 v[172:175], v168
	ds_read_b128 v[176:179], v169
	s_add_u32 s48, s46, 0xfffc0080
	s_addc_u32 s49, s47, -1
	s_cmp_eq_u32 s69, 12
	s_cselect_b32 s51, s41, s49
	s_cselect_b32 s50, s65, s48
	s_cselect_b32 s49, s31, s68
	s_cselect_b32 s48, s66, s67
	s_add_i32 m0, s26, 0xc000
	ds_read_b128 v[180:183], v141
	ds_read_b128 v[184:187], v141 offset:1024
	ds_read_b128 v[188:191], v141 offset:2048
	ds_read_b128 v[192:195], v141 offset:3072
	ds_read_b128 v[208:211], v141 offset:4096
	ds_read_b128 v[212:215], v141 offset:5120
	ds_read_b128 v[216:219], v141 offset:6144
	ds_read_b128 v[220:223], v141 offset:7168
	global_load_lds_dwordx4 v136, s[46:47]
	s_add_i32 m0, s26, 0xe000
	s_nop 0
	global_load_lds_dwordx4 v138, s[46:47]
	s_waitcnt vmcnt(8)
	s_waitcnt lgkmcnt(0)
	s_barrier
	s_setprio 1
	s_waitcnt lgkmcnt(0)
	v_mfma_f32_16x16x32_bf16 v[124:127], v[144:147], v[180:183], v[124:127]
	v_mfma_f32_16x16x32_bf16 v[120:123], v[152:155], v[180:183], v[120:123]
	v_mfma_f32_16x16x32_bf16 v[116:119], v[144:147], v[188:191], v[116:119]
	v_mfma_f32_16x16x32_bf16 v[112:115], v[152:155], v[188:191], v[112:115]
	v_mfma_f32_16x16x32_bf16 v[100:103], v[144:147], v[208:211], v[100:103]
	v_mfma_f32_16x16x32_bf16 v[96:99], v[152:155], v[208:211], v[96:99]
	v_mfma_f32_16x16x32_bf16 v[84:87], v[144:147], v[216:219], v[84:87]
	v_mfma_f32_16x16x32_bf16 v[80:83], v[152:155], v[216:219], v[80:83]
	v_mfma_f32_16x16x32_bf16 v[124:127], v[148:151], v[184:187], v[124:127]
	v_mfma_f32_16x16x32_bf16 v[120:123], v[156:159], v[184:187], v[120:123]
	v_mfma_f32_16x16x32_bf16 v[116:119], v[148:151], v[192:195], v[116:119]
	v_mfma_f32_16x16x32_bf16 v[112:115], v[156:159], v[192:195], v[112:115]
	v_mfma_f32_16x16x32_bf16 v[100:103], v[148:151], v[212:215], v[100:103]
	v_mfma_f32_16x16x32_bf16 v[96:99], v[156:159], v[212:215], v[96:99]
	v_mfma_f32_16x16x32_bf16 v[84:87], v[148:151], v[220:223], v[84:87]
	v_mfma_f32_16x16x32_bf16 v[80:83], v[156:159], v[220:223], v[80:83]
	s_setprio 0
	s_setprio 1
	v_mfma_f32_16x16x32_bf16 v[108:111], v[160:163], v[180:183], v[108:111]
	v_mfma_f32_16x16x32_bf16 v[104:107], v[172:175], v[180:183], v[104:107]
	v_mfma_f32_16x16x32_bf16 v[92:95], v[160:163], v[188:191], v[92:95]
	v_mfma_f32_16x16x32_bf16 v[88:91], v[172:175], v[188:191], v[88:91]
	v_mfma_f32_16x16x32_bf16 v[76:79], v[160:163], v[208:211], v[76:79]
	v_mfma_f32_16x16x32_bf16 v[72:75], v[172:175], v[208:211], v[72:75]
	v_mfma_f32_16x16x32_bf16 v[68:71], v[160:163], v[216:219], v[68:71]
	v_mfma_f32_16x16x32_bf16 v[64:67], v[172:175], v[216:219], v[64:67]
	v_mfma_f32_16x16x32_bf16 v[108:111], v[164:167], v[184:187], v[108:111]
	v_mfma_f32_16x16x32_bf16 v[104:107], v[176:179], v[184:187], v[104:107]
	v_mfma_f32_16x16x32_bf16 v[92:95], v[164:167], v[192:195], v[92:95]
	v_mfma_f32_16x16x32_bf16 v[88:91], v[176:179], v[192:195], v[88:91]
	v_mfma_f32_16x16x32_bf16 v[76:79], v[164:167], v[212:215], v[76:79]
	v_mfma_f32_16x16x32_bf16 v[72:75], v[176:179], v[212:215], v[72:75]
	v_mfma_f32_16x16x32_bf16 v[68:71], v[164:167], v[220:223], v[68:71]
	v_mfma_f32_16x16x32_bf16 v[64:67], v[176:179], v[220:223], v[64:67]
	s_setprio 0
	s_barrier
	s_mov_b32 m0, s1
	v_lshl_add_u64 v[168:169], s[48:49], 0, v[128:129]
	s_add_u32 s70, s48, 0x40000
	ds_read_b128 v[180:183], v141 offset:16384
	ds_read_b128 v[184:187], v141 offset:17408
	ds_read_b128 v[188:191], v141 offset:18432
	ds_read_b128 v[192:195], v141 offset:19456
	ds_read_b128 v[208:211], v141 offset:20480
	ds_read_b128 v[212:215], v141 offset:21504
	ds_read_b128 v[216:219], v141 offset:22528
	ds_read_b128 v[220:223], v141 offset:23552
	global_load_lds_dwordx4 v[168:169], off
	v_lshl_add_u64 v[196:197], s[48:49], 0, v[130:131]
	s_mov_b32 m0, s27
	s_addc_u32 s71, s49, 0
	global_load_lds_dwordx4 v[196:197], off
	s_mov_b32 m0, s36
	v_lshl_add_u64 v[224:225], s[50:51], 0, v[132:133]
	s_nop 4
	global_load_lds_dwordx4 v128, s[70:71]
	s_mov_b32 m0, s37
	s_nop 0
	global_load_lds_dwordx4 v130, s[70:71]
	v_lshl_add_u64 v[200:201], s[50:51], 0, v[134:135]
	s_mov_b32 m0, s26
	s_nop 0
	global_load_lds_dwordx4 v[200:201], off
	s_mov_b32 m0, s52
	s_nop 0
	global_load_lds_dwordx4 v[224:225], off
	s_waitcnt vmcnt(8)
	s_waitcnt lgkmcnt(0)
	s_barrier
; #define PG8_STAGE(bufoff, gbase, voff) do { _Pragma("unroll") for (int _i = 0; _i < 2; ++_i) \
;         __builtin_amdgcn_global_load_lds((const unsigned*)((const char*)(gbase) + (voff)[_i]), (LAS unsigned*)(lds + (bufoff) + ldsw + _i * 8192), 16, 0, 0); } while (0)
; #define PG8_LDA(dst, b, h) do { _Pragma("unroll") for (int m = 0; m < 4; ++m) _Pragma("unroll") for (int k = 0; k < 2; ++k) dst[m][k] = *(const LAS bf16x8*)(lds + PG8_SA(b, h) + aoff + m * 2048 + k * 1024); } while (0)
; #define PG8_LDB(dst, b, h) do { _Pragma("unroll") for (int n = 0; n < 2; ++n) _Pragma("unroll") for (int k = 0; k < 2; ++k) dst[n][k] = *(const LAS bf16x8*)(lds + PG8_SB(b, h) + boff + n * 2048 + k * 1024); } while (0)
; #define PG8_MMA(ai, bj, At, Bt) do { __builtin_amdgcn_s_setprio(1); _Pragma("unroll") for (int m = 0; m < 4; ++m) _Pragma("unroll") for (int n = 0; n < 2; ++n) _Pragma("unroll") for (int k = 0; k < 2; ++k) \
;         acc[ai][bj][m][n] = __builtin_amdgcn_mfma_f32_16x16x32_bf16(Bt[n][k], At[m][k], acc[ai][bj][m][n], 0, 0, 0); __builtin_amdgcn_s_setprio(0); } while (0)
; #define PG8_WAIT_V(n) asm volatile("s_waitcnt vmcnt(" #n ")" ::: "memory")
; #define PG8_WAIT_L(n) asm volatile("s_waitcnt lgkmcnt(" #n ")" ::: "memory")
; #define PG8_BAR __builtin_amdgcn_s_barrier()
; #define PG8_SCHED __builtin_amdgcn_sched_barrier(0)
; template <class Epi, class Sched, bool ALIGN_EPI = false, bool SP2 = false>
; __device__ __forceinline__ void gemm_phase(LAS unsigned char* lds, const Gemm g, const Sched& S, const Epi& E) {
;     ...
;             PG8_LDA(At, 0, 1); PG8_STAGE(PG8_SB(0, 0), b2, voffB); PG8_STAGE(PG8_SB(0, 1), b2 + hstep, voffB); PG8_STAGE(PG8_SA(0, 0), a2, voffA);
;             PG8_WAIT_V(8); PG8_WAIT_L(0); PG8_BAR; PG8_MMA(1, 0, At, B0); PG8_MMA(1, 1, At, B1); PG8_BAR; PG8_SCHED;
;             PG8_LDB(B0, 1, 0); PG8_LDB(B1, 1, 1); PG8_SCHED; PG8_LDA(At, 1, 0); PG8_STAGE(PG8_SA(0, 1), a2 + hstep, voffA);
;             PG8_WAIT_V(8); PG8_WAIT_L(0); PG8_BAR; PG8_MMA(0, 0, At, B0); PG8_MMA(0, 1, At, B1); PG8_BAR; PG8_SCHED;
;             PG8_LDA(At, 1, 1); PG8_STAGE(PG8_SB(1, 0), b3, voffB); PG8_STAGE(PG8_SB(1, 1), b3 + hstep, voffB); PG8_STAGE(PG8_SA(1, 0), a3, voffA);
	s_setprio 1
	s_waitcnt lgkmcnt(0)
	v_mfma_f32_16x16x32_bf16 v[60:63], v[144:147], v[180:183], v[60:63]
	v_mfma_f32_16x16x32_bf16 v[56:59], v[152:155], v[180:183], v[56:59]
	v_mfma_f32_16x16x32_bf16 v[52:55], v[144:147], v[188:191], v[52:55]
	v_mfma_f32_16x16x32_bf16 v[48:51], v[152:155], v[188:191], v[48:51]
	v_mfma_f32_16x16x32_bf16 v[36:39], v[144:147], v[208:211], v[36:39]
	v_mfma_f32_16x16x32_bf16 v[32:35], v[152:155], v[208:211], v[32:35]
	v_mfma_f32_16x16x32_bf16 v[20:23], v[144:147], v[216:219], v[20:23]
	v_mfma_f32_16x16x32_bf16 v[16:19], v[152:155], v[216:219], v[16:19]
	v_mfma_f32_16x16x32_bf16 v[60:63], v[148:151], v[184:187], v[60:63]
	v_mfma_f32_16x16x32_bf16 v[56:59], v[156:159], v[184:187], v[56:59]
	v_mfma_f32_16x16x32_bf16 v[52:55], v[148:151], v[192:195], v[52:55]
	v_mfma_f32_16x16x32_bf16 v[48:51], v[156:159], v[192:195], v[48:51]
	v_mfma_f32_16x16x32_bf16 v[36:39], v[148:151], v[212:215], v[36:39]
	v_mfma_f32_16x16x32_bf16 v[32:35], v[156:159], v[212:215], v[32:35]
	v_mfma_f32_16x16x32_bf16 v[20:23], v[148:151], v[220:223], v[20:23]
	v_mfma_f32_16x16x32_bf16 v[16:19], v[156:159], v[220:223], v[16:19]
	s_setprio 0
	s_setprio 1
	v_mfma_f32_16x16x32_bf16 v[44:47], v[160:163], v[180:183], v[44:47]
	v_mfma_f32_16x16x32_bf16 v[40:43], v[172:175], v[180:183], v[40:43]
	v_mfma_f32_16x16x32_bf16 v[28:31], v[160:163], v[188:191], v[28:31]
	v_mfma_f32_16x16x32_bf16 v[24:27], v[172:175], v[188:191], v[24:27]
	v_mfma_f32_16x16x32_bf16 v[12:15], v[160:163], v[208:211], v[12:15]
	v_mfma_f32_16x16x32_bf16 v[8:11], v[172:175], v[208:211], v[8:11]
	v_mfma_f32_16x16x32_bf16 v[4:7], v[160:163], v[216:219], v[4:7]
	v_mfma_f32_16x16x32_bf16 v[0:3], v[172:175], v[216:219], v[0:3]
	v_mfma_f32_16x16x32_bf16 v[44:47], v[164:167], v[184:187], v[44:47]
	v_mfma_f32_16x16x32_bf16 v[40:43], v[176:179], v[184:187], v[40:43]
	v_mfma_f32_16x16x32_bf16 v[28:31], v[164:167], v[192:195], v[28:31]
	v_mfma_f32_16x16x32_bf16 v[24:27], v[176:179], v[192:195], v[24:27]
	v_mfma_f32_16x16x32_bf16 v[12:15], v[164:167], v[212:215], v[12:15]
	v_mfma_f32_16x16x32_bf16 v[8:11], v[176:179], v[212:215], v[8:11]
	v_mfma_f32_16x16x32_bf16 v[4:7], v[164:167], v[220:223], v[4:7]
	v_mfma_f32_16x16x32_bf16 v[0:3], v[176:179], v[220:223], v[0:3]
	s_setprio 0
	s_barrier
	v_or_b32_e32 v144, 0x18000, v142
	v_add_u32_e32 v148, 0x18400, v142
	v_add_u32_e32 v152, 0x18800, v142
	v_add_u32_e32 v156, 0x18c00, v142
	v_or_b32_e32 v160, 0x1c000, v142
	v_add_u32_e32 v164, 0x1c400, v142
	v_add_u32_e32 v172, 0x1c800, v142
	v_add_u32_e32 v176, 0x1cc00, v142
	ds_read_b128 v[144:147], v144
	ds_read_b128 v[148:151], v148
	ds_read_b128 v[152:155], v152
	ds_read_b128 v[156:159], v156
	ds_read_b128 v[160:163], v160
	ds_read_b128 v[164:167], v164
	ds_read_b128 v[172:175], v172
	ds_read_b128 v[176:179], v176
	s_add_u32 s50, s50, 0x40000
	s_addc_u32 s51, s51, 0
	s_mov_b32 m0, s53
	ds_read_b128 v[180:183], v141 offset:32768
	ds_read_b128 v[184:187], v141 offset:33792
	ds_read_b128 v[188:191], v141 offset:34816
	ds_read_b128 v[192:195], v141 offset:35840
	ds_read_b128 v[208:211], v141 offset:36864
	ds_read_b128 v[212:215], v141 offset:37888
	ds_read_b128 v[216:219], v141 offset:38912
	ds_read_b128 v[220:223], v141 offset:39936
	global_load_lds_dwordx4 v134, s[50:51]
	v_lshl_add_u64 v[226:227], s[50:51], 0, v[132:133]
	s_mov_b32 m0, s54
	s_nop 0
	global_load_lds_dwordx4 v[226:227], off
	s_waitcnt vmcnt(8)
	s_waitcnt lgkmcnt(0)
	s_barrier
	s_setprio 1
	s_waitcnt lgkmcnt(0)
	v_mfma_f32_16x16x32_bf16 v[124:127], v[144:147], v[180:183], v[124:127]
	v_mfma_f32_16x16x32_bf16 v[120:123], v[152:155], v[180:183], v[120:123]
	v_mfma_f32_16x16x32_bf16 v[116:119], v[144:147], v[188:191], v[116:119]
	v_mfma_f32_16x16x32_bf16 v[112:115], v[152:155], v[188:191], v[112:115]
	v_mfma_f32_16x16x32_bf16 v[100:103], v[144:147], v[208:211], v[100:103]
	v_mfma_f32_16x16x32_bf16 v[96:99], v[152:155], v[208:211], v[96:99]
	v_mfma_f32_16x16x32_bf16 v[84:87], v[144:147], v[216:219], v[84:87]
	v_mfma_f32_16x16x32_bf16 v[80:83], v[152:155], v[216:219], v[80:83]
	v_mfma_f32_16x16x32_bf16 v[124:127], v[148:151], v[184:187], v[124:127]
	v_mfma_f32_16x16x32_bf16 v[120:123], v[156:159], v[184:187], v[120:123]
	v_mfma_f32_16x16x32_bf16 v[116:119], v[148:151], v[192:195], v[116:119]
	v_mfma_f32_16x16x32_bf16 v[112:115], v[156:159], v[192:195], v[112:115]
	v_mfma_f32_16x16x32_bf16 v[100:103], v[148:151], v[212:215], v[100:103]
	v_mfma_f32_16x16x32_bf16 v[96:99], v[156:159], v[212:215], v[96:99]
	v_mfma_f32_16x16x32_bf16 v[84:87], v[148:151], v[220:223], v[84:87]
	v_mfma_f32_16x16x32_bf16 v[80:83], v[156:159], v[220:223], v[80:83]
	s_setprio 0
	s_setprio 1
	v_mfma_f32_16x16x32_bf16 v[108:111], v[160:163], v[180:183], v[108:111]
	v_mfma_f32_16x16x32_bf16 v[104:107], v[172:175], v[180:183], v[104:107]
	v_mfma_f32_16x16x32_bf16 v[92:95], v[160:163], v[188:191], v[92:95]
	v_mfma_f32_16x16x32_bf16 v[88:91], v[172:175], v[188:191], v[88:91]
	v_mfma_f32_16x16x32_bf16 v[76:79], v[160:163], v[208:211], v[76:79]
	v_mfma_f32_16x16x32_bf16 v[72:75], v[172:175], v[208:211], v[72:75]
	v_mfma_f32_16x16x32_bf16 v[68:71], v[160:163], v[216:219], v[68:71]
	v_mfma_f32_16x16x32_bf16 v[64:67], v[172:175], v[216:219], v[64:67]
	v_mfma_f32_16x16x32_bf16 v[108:111], v[164:167], v[184:187], v[108:111]
	v_mfma_f32_16x16x32_bf16 v[104:107], v[176:179], v[184:187], v[104:107]
	v_mfma_f32_16x16x32_bf16 v[92:95], v[164:167], v[192:195], v[92:95]
	v_mfma_f32_16x16x32_bf16 v[88:91], v[176:179], v[192:195], v[88:91]
	v_mfma_f32_16x16x32_bf16 v[76:79], v[164:167], v[212:215], v[76:79]
	v_mfma_f32_16x16x32_bf16 v[72:75], v[176:179], v[212:215], v[72:75]
	v_mfma_f32_16x16x32_bf16 v[68:71], v[164:167], v[220:223], v[68:71]
	v_mfma_f32_16x16x32_bf16 v[64:67], v[176:179], v[220:223], v[64:67]
	s_setprio 0
	s_barrier
; #define PG8_STAGE(bufoff, gbase, voff) do { _Pragma("unroll") for (int _i = 0; _i < 2; ++_i) \
;         __builtin_amdgcn_global_load_lds((const unsigned*)((const char*)(gbase) + (voff)[_i]), (LAS unsigned*)(lds + (bufoff) + ldsw + _i * 8192), 16, 0, 0); } while (0)
; #define PG8_LDA(dst, b, h) do { _Pragma("unroll") for (int m = 0; m < 4; ++m) _Pragma("unroll") for (int k = 0; k < 2; ++k) dst[m][k] = *(const LAS bf16x8*)(lds + PG8_SA(b, h) + aoff + m * 2048 + k * 1024); } while (0)
; #define PG8_LDB(dst, b, h) do { _Pragma("unroll") for (int n = 0; n < 2; ++n) _Pragma("unroll") for (int k = 0; k < 2; ++k) dst[n][k] = *(const LAS bf16x8*)(lds + PG8_SB(b, h) + boff + n * 2048 + k * 1024); } while (0)
; #define PG8_MMA(ai, bj, At, Bt) do { __builtin_amdgcn_s_setprio(1); _Pragma("unroll") for (int m = 0; m < 4; ++m) _Pragma("unroll") for (int n = 0; n < 2; ++n) _Pragma("unroll") for (int k = 0; k < 2; ++k) \
;         acc[ai][bj][m][n] = __builtin_amdgcn_mfma_f32_16x16x32_bf16(Bt[n][k], At[m][k], acc[ai][bj][m][n], 0, 0, 0); __builtin_amdgcn_s_setprio(0); } while (0)
; #define PG8_WAIT_V(n) asm volatile("s_waitcnt vmcnt(" #n ")" ::: "memory")
; #define PG8_WAIT_L(n) asm volatile("s_waitcnt lgkmcnt(" #n ")" ::: "memory")
; #define PG8_BAR __builtin_amdgcn_s_barrier()
; #define PG8_SCHED __builtin_amdgcn_sched_barrier(0)
; template <class Epi, class Sched, bool ALIGN_EPI = false, bool SP2 = false>
; __device__ __forceinline__ void gemm_phase(LAS unsigned char* lds, const Gemm g, const Sched& S, const Epi& E) {
;     ...
;             PG8_LDB(B0, 1, 0); PG8_LDB(B1, 1, 1); PG8_SCHED; PG8_LDA(At, 1, 0); PG8_STAGE(PG8_SA(0, 1), a2 + hstep, voffA);
;             PG8_WAIT_V(8); PG8_WAIT_L(0); PG8_BAR; PG8_MMA(0, 0, At, B0); PG8_MMA(0, 1, At, B1); PG8_BAR; PG8_SCHED;
;             PG8_LDA(At, 1, 1); PG8_STAGE(PG8_SB(1, 0), b3, voffB); PG8_STAGE(PG8_SB(1, 1), b3 + hstep, voffB); PG8_STAGE(PG8_SA(1, 0), a3, voffA);
;             PG8_WAIT_V(8); PG8_WAIT_L(0); PG8_BAR; PG8_MMA(1, 0, At, B0); PG8_MMA(1, 1, At, B1); PG8_BAR; PG8_SCHED;
	s_mov_b32 m0, s57
	v_lshl_add_u64 v[168:169], v[168:169], 0, s[24:25]
	s_add_u32 s48, s48, 0x40080
	ds_read_b128 v[180:183], v141 offset:49152
	ds_read_b128 v[184:187], v141 offset:50176
	ds_read_b128 v[188:191], v141 offset:51200
	ds_read_b128 v[192:195], v141 offset:52224
	ds_read_b128 v[208:211], v141 offset:53248
	ds_read_b128 v[212:215], v141 offset:54272
	ds_read_b128 v[216:219], v141 offset:55296
	ds_read_b128 v[220:223], v141 offset:56320
	global_load_lds_dwordx4 v[168:169], off
	v_lshl_add_u64 v[168:169], v[196:197], 0, s[24:25]
	s_mov_b32 m0, s58
	s_addc_u32 s49, s49, 0
	global_load_lds_dwordx4 v[168:169], off
	s_mov_b32 m0, s61
	s_nop 0
	s_nop 4
	global_load_lds_dwordx4 v128, s[48:49]
	v_lshl_add_u64 v[168:169], s[48:49], 0, v[130:131]
	s_mov_b32 m0, s62
	s_nop 0
	global_load_lds_dwordx4 v[168:169], off
	v_lshl_add_u64 v[168:169], v[200:201], 0, s[24:25]
	s_mov_b32 m0, s59
	s_nop 0
	global_load_lds_dwordx4 v[168:169], off
	v_lshl_add_u64 v[168:169], v[224:225], 0, s[24:25]
	s_mov_b32 m0, s60
	s_nop 0
	global_load_lds_dwordx4 v[168:169], off
	s_waitcnt vmcnt(8)
	s_waitcnt lgkmcnt(0)
	s_barrier
	s_setprio 1
	s_waitcnt lgkmcnt(0)
	v_mfma_f32_16x16x32_bf16 v[60:63], v[144:147], v[180:183], v[60:63]
	v_mfma_f32_16x16x32_bf16 v[56:59], v[152:155], v[180:183], v[56:59]
	v_mfma_f32_16x16x32_bf16 v[52:55], v[144:147], v[188:191], v[52:55]
	v_mfma_f32_16x16x32_bf16 v[48:51], v[152:155], v[188:191], v[48:51]
	v_mfma_f32_16x16x32_bf16 v[36:39], v[144:147], v[208:211], v[36:39]
	v_mfma_f32_16x16x32_bf16 v[32:35], v[152:155], v[208:211], v[32:35]
	v_mfma_f32_16x16x32_bf16 v[20:23], v[144:147], v[216:219], v[20:23]
	v_mfma_f32_16x16x32_bf16 v[16:19], v[152:155], v[216:219], v[16:19]
	v_mfma_f32_16x16x32_bf16 v[60:63], v[148:151], v[184:187], v[60:63]
	v_mfma_f32_16x16x32_bf16 v[56:59], v[156:159], v[184:187], v[56:59]
	v_mfma_f32_16x16x32_bf16 v[52:55], v[148:151], v[192:195], v[52:55]
	v_mfma_f32_16x16x32_bf16 v[48:51], v[156:159], v[192:195], v[48:51]
	v_mfma_f32_16x16x32_bf16 v[36:39], v[148:151], v[212:215], v[36:39]
	v_mfma_f32_16x16x32_bf16 v[32:35], v[156:159], v[212:215], v[32:35]
	v_mfma_f32_16x16x32_bf16 v[20:23], v[148:151], v[220:223], v[20:23]
	v_mfma_f32_16x16x32_bf16 v[16:19], v[156:159], v[220:223], v[16:19]
	s_setprio 0
	s_setprio 1
	v_mfma_f32_16x16x32_bf16 v[44:47], v[160:163], v[180:183], v[44:47]
	v_mfma_f32_16x16x32_bf16 v[40:43], v[172:175], v[180:183], v[40:43]
	v_mfma_f32_16x16x32_bf16 v[28:31], v[160:163], v[188:191], v[28:31]
	v_mfma_f32_16x16x32_bf16 v[24:27], v[172:175], v[188:191], v[24:27]
	v_mfma_f32_16x16x32_bf16 v[12:15], v[160:163], v[208:211], v[12:15]
	v_mfma_f32_16x16x32_bf16 v[8:11], v[172:175], v[208:211], v[8:11]
	v_mfma_f32_16x16x32_bf16 v[4:7], v[160:163], v[216:219], v[4:7]
	v_mfma_f32_16x16x32_bf16 v[0:3], v[172:175], v[216:219], v[0:3]
	v_mfma_f32_16x16x32_bf16 v[44:47], v[164:167], v[184:187], v[44:47]
	v_mfma_f32_16x16x32_bf16 v[40:43], v[176:179], v[184:187], v[40:43]
	v_mfma_f32_16x16x32_bf16 v[28:31], v[164:167], v[192:195], v[28:31]
	v_mfma_f32_16x16x32_bf16 v[24:27], v[176:179], v[192:195], v[24:27]
	v_mfma_f32_16x16x32_bf16 v[12:15], v[164:167], v[212:215], v[12:15]
	v_mfma_f32_16x16x32_bf16 v[8:11], v[176:179], v[212:215], v[8:11]
	v_mfma_f32_16x16x32_bf16 v[4:7], v[164:167], v[220:223], v[4:7]
	v_mfma_f32_16x16x32_bf16 v[0:3], v[176:179], v[220:223], v[0:3]
	s_setprio 0
	s_barrier
	s_add_i32 s69, s69, 2
	s_add_u32 s46, s46, 0x100
	s_addc_u32 s47, s47, 0
	s_add_u32 s67, s67, 0x100
	s_addc_u32 s68, s68, 0
	s_cmp_gt_u32 s69, 13
	s_cbranch_scc0 .LBB0_153
; DI unsigned pack2(float lo, float hi) { f32x2 v = {lo, hi}; bf16x2_t b = __builtin_convertvector(v, bf16x2_t); return __builtin_bit_cast(unsigned, b); }
; #define PG8_WAIT_V(n) asm volatile("s_waitcnt vmcnt(" #n ")" ::: "memory")
; #define PG8_BAR __builtin_amdgcn_s_barrier()
; template <class Epi, class Sched, bool ALIGN_EPI = false, bool SP2 = false>
; __device__ __forceinline__ void gemm_phase(LAS unsigned char* lds, const Gemm g, const Sched& S, const Epi& E) {
;     ...
;         if (!has_next) break;
; #pragma unroll
;         for (int a = 0; a < 2; ++a)
; #pragma unroll
;             for (int b = 0; b < 2; ++b)
; #pragma unroll
;                 for (int m = 0; m < 4; ++m)
; #pragma unroll
;                     for (int n = 0; n < 2; ++n) acc[a][b][m][n] = (f32x4){0.f, 0.f, 0.f, 0.f};
;         cur = nxt; cA = nA; cB = nB; ++ui;
;         if constexpr (ALIGN_EPI) { if (wr == 1) PG8_BAR; }
;     }
;     PG8_WAIT_V(0);
;     if constexpr (!ALIGN_EPI) { if (wr == 0) PG8_BAR; }
;     DI void operator()(const f32x4 (&acc)[2][2][4][2], const Unit& u, int wr, int wc, int fr, int fq) const {
;         const int row0 = u.pm * BM + wr * 64 + fr, col0 = u.pn * BM + wc * 32 + 8 * fq;
; #pragma unroll
;         for (int ai = 0; ai < 2; ++ai)
; #pragma unroll
;             for (int m = 0; m < 4; ++m) {
;                 bf16_t* rowp = O + (size_t)(row0 + ai * HALF + m * 16) * D + col0;
; #pragma unroll
;                 for (int bj = 0; bj < 2; ++bj) {
;                     const f32x4 v0 = acc[ai][bj][m][0], v1 = acc[ai][bj][m][1];
;                     u32x4 w; w.x = pack2(v0[0], v0[1]); w.y = pack2(v0[2], v0[3]); w.z = pack2(v1[0], v1[1]); w.w = pack2(v1[2], v1[3]);
;                     *(u32x4*)(rowp + bj * HALF) = w;
;                 }
;             }
;     }
	v_lshl_add_u32 v144, s0, 8, v140
	v_lshl_or_b32 v146, s64, 8, v143
	v_ashrrev_i32_e32 v145, 31, v144
	v_ashrrev_i32_e32 v147, 31, v146
	v_lshlrev_b64 v[148:149], 11, v[144:145]
	v_lshl_add_u64 v[148:149], s[80:81], 0, v[148:149]
	v_lshlrev_b64 v[146:147], 1, v[146:147]
	v_lshl_add_u64 v[148:149], v[148:149], 0, v[146:147]
	s_mov_b32 s0, 0x40000
	s_mov_b64 s[46:47], 0x40000
	v_cvt_pk_bf16_f32 v60, v60, v61
	v_cvt_pk_bf16_f32 v61, v62, v63
	v_cvt_pk_bf16_f32 v62, v56, v57
	v_add_co_u32_e32 v56, vcc, s0, v148
	v_cvt_pk_bf16_f32 v68, v68, v69
	v_cvt_pk_bf16_f32 v69, v70, v71
	v_cvt_pk_bf16_f32 v70, v64, v65
	v_lshl_add_u64 v[64:65], v[148:149], 0, s[46:47]
	v_addc_co_u32_e32 v57, vcc, 0, v149, vcc
	v_cvt_pk_bf16_f32 v44, v44, v45
	v_cvt_pk_bf16_f32 v45, v46, v47
	v_cvt_pk_bf16_f32 v46, v40, v41
	v_cvt_pk_bf16_f32 v47, v42, v43
	s_mov_b32 s0, 0x48000
	v_cvt_pk_bf16_f32 v108, v108, v109
	v_cvt_pk_bf16_f32 v109, v110, v111
	v_cvt_pk_bf16_f32 v110, v104, v105
	v_or_b32_e32 v104, 16, v144
	global_store_dwordx4 v[64:65], v[44:47], off offset:256
	s_mov_b64 s[46:47], 0x48000
	v_ashrrev_i32_e32 v105, 31, v104
	v_add_co_u32_e32 v46, vcc, s0, v148
	v_cvt_pk_bf16_f32 v92, v92, v93
	v_cvt_pk_bf16_f32 v93, v94, v95
	v_cvt_pk_bf16_f32 v94, v88, v89
	v_or_b32_e32 v88, 32, v144
	v_lshl_add_u64 v[44:45], v[148:149], 0, s[46:47]
	v_addc_co_u32_e32 v47, vcc, 0, v149, vcc
	v_cvt_pk_bf16_f32 v28, v28, v29
	v_cvt_pk_bf16_f32 v29, v30, v31
	v_cvt_pk_bf16_f32 v30, v24, v25
	v_cvt_pk_bf16_f32 v31, v26, v27
	s_mov_b32 s0, 0x50000
	v_lshlrev_b64 v[104:105], 11, v[104:105]
	v_ashrrev_i32_e32 v89, 31, v88
	v_cvt_pk_bf16_f32 v76, v76, v77
	v_cvt_pk_bf16_f32 v77, v78, v79
	v_cvt_pk_bf16_f32 v78, v72, v73
	v_or_b32_e32 v72, 48, v144
	global_store_dwordx4 v[44:45], v[28:31], off offset:256
	s_mov_b64 s[46:47], 0x50000
	v_cvt_pk_bf16_f32 v111, v106, v107
	v_add_co_u32_e32 v30, vcc, s0, v148
	v_lshl_add_u64 v[104:105], s[80:81], 0, v[104:105]
	v_lshlrev_b64 v[88:89], 11, v[88:89]
	v_ashrrev_i32_e32 v73, 31, v72
	v_lshl_add_u64 v[28:29], v[148:149], 0, s[46:47]
	v_addc_co_u32_e32 v31, vcc, 0, v149, vcc
	v_cvt_pk_bf16_f32 v12, v12, v13
	v_cvt_pk_bf16_f32 v13, v14, v15
	v_cvt_pk_bf16_f32 v14, v8, v9
	v_cvt_pk_bf16_f32 v15, v10, v11
	s_mov_b32 s0, 0x58000
	global_store_dwordx4 v[148:149], v[108:111], off offset:256
	v_cvt_pk_bf16_f32 v95, v90, v91
	v_lshl_add_u64 v[88:89], s[80:81], 0, v[88:89]
	v_lshl_add_u64 v[108:109], v[104:105], 0, v[146:147]
	v_lshlrev_b64 v[72:73], 11, v[72:73]
	global_store_dwordx4 v[28:29], v[12:15], off offset:256
	global_store_dwordx4 v[108:109], v[92:95], off offset:256
	v_cvt_pk_bf16_f32 v79, v74, v75
	v_add_co_u32_e32 v14, vcc, s0, v148
	v_lshl_add_u64 v[92:93], v[88:89], 0, v[146:147]
	v_lshl_add_u64 v[72:73], s[80:81], 0, v[72:73]
	s_mov_b64 s[46:47], 0x58000
	v_addc_co_u32_e32 v15, vcc, 0, v149, vcc
	v_cvt_pk_bf16_f32 v124, v124, v125
	v_cvt_pk_bf16_f32 v125, v126, v127
	v_cvt_pk_bf16_f32 v126, v120, v121
	v_cvt_pk_bf16_f32 v127, v122, v123
	v_cvt_pk_bf16_f32 v104, v116, v117
	v_cvt_pk_bf16_f32 v105, v118, v119
	v_cvt_pk_bf16_f32 v106, v112, v113
	v_cvt_pk_bf16_f32 v107, v114, v115
	v_cvt_pk_bf16_f32 v88, v100, v101
	v_cvt_pk_bf16_f32 v89, v102, v103
	v_cvt_pk_bf16_f32 v90, v96, v97
	v_cvt_pk_bf16_f32 v91, v98, v99
	global_store_dwordx4 v[92:93], v[76:79], off offset:256
	v_cvt_pk_bf16_f32 v74, v80, v81
	v_cvt_pk_bf16_f32 v75, v82, v83
	v_lshl_add_u64 v[76:77], v[72:73], 0, v[146:147]
	v_cvt_pk_bf16_f32 v72, v84, v85
	v_cvt_pk_bf16_f32 v73, v86, v87
	v_cvt_pk_bf16_f32 v71, v66, v67
	v_cvt_pk_bf16_f32 v63, v58, v59
	v_cvt_pk_bf16_f32 v40, v52, v53
	v_cvt_pk_bf16_f32 v41, v54, v55
	v_cvt_pk_bf16_f32 v42, v48, v49
	v_cvt_pk_bf16_f32 v43, v50, v51
	v_cvt_pk_bf16_f32 v24, v36, v37
	v_cvt_pk_bf16_f32 v25, v38, v39
	v_cvt_pk_bf16_f32 v26, v32, v33
	v_cvt_pk_bf16_f32 v27, v34, v35
	v_lshl_add_u64 v[12:13], v[148:149], 0, s[46:47]
	v_cvt_pk_bf16_f32 v8, v20, v21
	v_cvt_pk_bf16_f32 v9, v22, v23
	v_cvt_pk_bf16_f32 v10, v16, v17
	v_cvt_pk_bf16_f32 v11, v18, v19
	v_cvt_pk_bf16_f32 v4, v4, v5
	v_cvt_pk_bf16_f32 v5, v6, v7
	v_cvt_pk_bf16_f32 v6, v0, v1
	v_cvt_pk_bf16_f32 v7, v2, v3
	s_and_b64 vcc, exec, s[38:39]
	s_mov_b32 s64, s30
	s_mov_b32 s0, s40
	s_mov_b64 s[48:49], s[44:45]
	s_mov_b64 s[46:47], s[42:43]
	global_store_dwordx4 v[148:149], v[124:127], off
	global_store_dwordx4 v[108:109], v[104:107], off
	global_store_dwordx4 v[92:93], v[88:91], off
	global_store_dwordx4 v[76:77], v[72:75], off
	global_store_dwordx4 v[76:77], v[68:71], off offset:256
	global_store_dwordx4 v[56:57], v[60:63], off
	global_store_dwordx4 v[46:47], v[40:43], off
	global_store_dwordx4 v[30:31], v[24:27], off
	global_store_dwordx4 v[14:15], v[8:11], off
	global_store_dwordx4 v[12:13], v[4:7], off offset:256
	s_cbranch_vccz .LBB0_150
	s_waitcnt vmcnt(0)
	s_cmpk_gt_u32 s2, 0xff
	s_cbranch_scc1 .LBB0_157
	s_barrier

; #define PG8_STAGE(bufoff, gbase, voff) do { _Pragma("unroll") for (int _i = 0; _i < 2; ++_i) \
;         __builtin_amdgcn_global_load_lds((const unsigned*)((const char*)(gbase) + (voff)[_i]), (LAS unsigned*)(lds + (bufoff) + ldsw + _i * 8192), 16, 0, 0); } while (0)
; #define PG8_LDA(dst, b, h) do { _Pragma("unroll") for (int m = 0; m < 4; ++m) _Pragma("unroll") for (int k = 0; k < 2; ++k) dst[m][k] = *(const LAS bf16x8*)(lds + PG8_SA(b, h) + aoff + m * 2048 + k * 1024); } while (0)
; #define PG8_LDB(dst, b, h) do { _Pragma("unroll") for (int n = 0; n < 2; ++n) _Pragma("unroll") for (int k = 0; k < 2; ++k) dst[n][k] = *(const LAS bf16x8*)(lds + PG8_SB(b, h) + boff + n * 2048 + k * 1024); } while (0)
; #define PG8_MMA(ai, bj, At, Bt) do { __builtin_amdgcn_s_setprio(1); _Pragma("unroll") for (int m = 0; m < 4; ++m) _Pragma("unroll") for (int n = 0; n < 2; ++n) _Pragma("unroll") for (int k = 0; k < 2; ++k) \
;         acc[ai][bj][m][n] = __builtin_amdgcn_mfma_f32_16x16x32_bf16(Bt[n][k], At[m][k], acc[ai][bj][m][n], 0, 0, 0); __builtin_amdgcn_s_setprio(0); } while (0)
; #define PG8_WAIT_V(n) asm volatile("s_waitcnt vmcnt(" #n ")" ::: "memory")
; #define PG8_WAIT_L(n) asm volatile("s_waitcnt lgkmcnt(" #n ")" ::: "memory")
; template <class Epi, class Sched, bool ALIGN_EPI = false, bool SP2 = false>
; __device__ __forceinline__ void gemm_phase(LAS unsigned char* lds, const Gemm g, const Sched& S, const Epi& E) {
;     ...
;         for (int t = 0; t < nt; t += 2) {
;             const bool last = (t == nt - 2);
;             const char* a1 = cA + (size_t)(t + 1) * kstep;
;             const char* a2 = last ? nA : cA + (size_t)(t + 2) * kstep; const char* b2 = last ? nB : cB + (size_t)(t + 2) * kstep;
;             const char* a3 = a2 + kstep; const char* b3 = b2 + kstep;
;             if (last && has_next) S.a_ready(nxt);
;             if constexpr (SP2) {
;             PG8_LDB(B0, 0, 0); PG8_LDB(B1, 0, 1); PG8_SCHED; PG8_LDA(At, 0, 0); PG8_STAGE(PG8_SA(1, 1), a1 + hstep, voffA);
;             PG8_WAIT_V(8); PG8_WAIT_L(0); PG8_BAR; PG8_MMA(0, 0, At, B0); PG8_MMA(0, 1, At, B1); PG8_BAR; PG8_SCHED;
;             PG8_LDA(At, 0, 1); PG8_STAGE(PG8_SB(0, 0), b2, voffB); PG8_STAGE(PG8_SB(0, 1), b2 + hstep, voffB); PG8_STAGE(PG8_SA(0, 0), a2, voffA);
;             PG8_WAIT_V(8); PG8_WAIT_L(0); PG8_BAR; PG8_MMA(1, 0, At, B0); PG8_MMA(1, 1, At, B1); PG8_BAR; PG8_SCHED;
.LBB0_334:
	v_or_b32_e32 v64, 0x10000, v163
	v_add_u32_e32 v68, 0x10400, v163
	v_add_u32_e32 v72, 0x10800, v163
	v_add_u32_e32 v80, 0x10c00, v163
	v_or_b32_e32 v156, 0x14000, v163
	v_add_u32_e32 v164, 0x14400, v163
	v_add_u32_e32 v168, 0x14800, v163
	ds_read_b128 v[64:67], v64
	ds_read_b128 v[68:71], v68
	ds_read_b128 v[72:75], v72
	ds_read_b128 v[80:83], v80
	ds_read_b128 v[156:159], v156
	ds_read_b128 v[164:167], v164
	v_add_u32_e32 v169, 0x14c00, v163
	ds_read_b128 v[172:175], v168
	ds_read_b128 v[176:179], v169
	s_add_u32 s44, s42, 0xfffc0080
	s_addc_u32 s45, s43, -1
	s_cmp_eq_u32 s55, 12
	s_cselect_b32 s51, s35, s45
	s_cselect_b32 s50, s41, s44
	s_cselect_b32 s45, s31, s54
	s_cselect_b32 s44, s52, s53
	s_add_i32 m0, s68, 0xc000
	ds_read_b128 v[180:183], v162
	ds_read_b128 v[184:187], v162 offset:1024
	ds_read_b128 v[188:191], v162 offset:2048
	ds_read_b128 v[192:195], v162 offset:3072
	ds_read_b128 v[208:211], v162 offset:4096
	ds_read_b128 v[212:215], v162 offset:5120
	ds_read_b128 v[216:219], v162 offset:6144
	ds_read_b128 v[220:223], v162 offset:7168
	global_load_lds_dwordx4 v152, s[42:43]
	s_add_i32 m0, s68, 0xe000
	s_nop 0
	global_load_lds_dwordx4 v154, s[42:43]
	s_waitcnt vmcnt(8)
	s_waitcnt lgkmcnt(0)
	s_barrier
	s_setprio 1
	s_waitcnt lgkmcnt(0)
	v_mfma_f32_16x16x32_bf16 v[142:145], v[64:67], v[180:183], v[142:145]
	v_mfma_f32_16x16x32_bf16 v[138:141], v[72:75], v[180:183], v[138:141]
	v_mfma_f32_16x16x32_bf16 v[124:127], v[64:67], v[188:191], v[124:127]
	v_mfma_f32_16x16x32_bf16 v[120:123], v[72:75], v[188:191], v[120:123]
	v_mfma_f32_16x16x32_bf16 v[108:111], v[64:67], v[208:211], v[108:111]
	v_mfma_f32_16x16x32_bf16 v[104:107], v[72:75], v[208:211], v[104:107]
	v_mfma_f32_16x16x32_bf16 v[92:95], v[64:67], v[216:219], v[92:95]
	v_mfma_f32_16x16x32_bf16 v[88:91], v[72:75], v[216:219], v[88:91]
	v_mfma_f32_16x16x32_bf16 v[142:145], v[68:71], v[184:187], v[142:145]
	v_mfma_f32_16x16x32_bf16 v[138:141], v[80:83], v[184:187], v[138:141]
	v_mfma_f32_16x16x32_bf16 v[124:127], v[68:71], v[192:195], v[124:127]
	v_mfma_f32_16x16x32_bf16 v[120:123], v[80:83], v[192:195], v[120:123]
	v_mfma_f32_16x16x32_bf16 v[108:111], v[68:71], v[212:215], v[108:111]
	v_mfma_f32_16x16x32_bf16 v[104:107], v[80:83], v[212:215], v[104:107]
	v_mfma_f32_16x16x32_bf16 v[92:95], v[68:71], v[220:223], v[92:95]
	v_mfma_f32_16x16x32_bf16 v[88:91], v[80:83], v[220:223], v[88:91]
	s_setprio 0
	s_setprio 1
	v_mfma_f32_16x16x32_bf16 v[134:137], v[156:159], v[180:183], v[134:137]
	v_mfma_f32_16x16x32_bf16 v[130:133], v[172:175], v[180:183], v[130:133]
	v_mfma_f32_16x16x32_bf16 v[116:119], v[156:159], v[188:191], v[116:119]
	v_mfma_f32_16x16x32_bf16 v[112:115], v[172:175], v[188:191], v[112:115]
	v_mfma_f32_16x16x32_bf16 v[100:103], v[156:159], v[208:211], v[100:103]
	v_mfma_f32_16x16x32_bf16 v[96:99], v[172:175], v[208:211], v[96:99]
	v_mfma_f32_16x16x32_bf16 v[84:87], v[156:159], v[216:219], v[84:87]
	v_mfma_f32_16x16x32_bf16 v[76:79], v[172:175], v[216:219], v[76:79]
	v_mfma_f32_16x16x32_bf16 v[134:137], v[164:167], v[184:187], v[134:137]
	v_mfma_f32_16x16x32_bf16 v[130:133], v[176:179], v[184:187], v[130:133]
	v_mfma_f32_16x16x32_bf16 v[116:119], v[164:167], v[192:195], v[116:119]
	v_mfma_f32_16x16x32_bf16 v[112:115], v[176:179], v[192:195], v[112:115]
	v_mfma_f32_16x16x32_bf16 v[100:103], v[164:167], v[212:215], v[100:103]
	v_mfma_f32_16x16x32_bf16 v[96:99], v[176:179], v[212:215], v[96:99]
	v_mfma_f32_16x16x32_bf16 v[84:87], v[164:167], v[220:223], v[84:87]
	v_mfma_f32_16x16x32_bf16 v[76:79], v[176:179], v[220:223], v[76:79]
	s_setprio 0
	s_barrier
	s_mov_b32 m0, s69
	v_lshl_add_u64 v[168:169], s[44:45], 0, v[128:129]
	s_add_u32 s58, s44, 0x40000
	ds_read_b128 v[180:183], v162 offset:16384
	ds_read_b128 v[184:187], v162 offset:17408
	ds_read_b128 v[188:191], v162 offset:18432
	ds_read_b128 v[192:195], v162 offset:19456
	ds_read_b128 v[208:211], v162 offset:20480
	ds_read_b128 v[212:215], v162 offset:21504
	ds_read_b128 v[216:219], v162 offset:22528
	ds_read_b128 v[220:223], v162 offset:23552
	global_load_lds_dwordx4 v[168:169], off
	v_lshl_add_u64 v[196:197], s[44:45], 0, v[150:151]
	s_mov_b32 m0, s72
	s_addc_u32 s59, s45, 0
	global_load_lds_dwordx4 v[196:197], off
	s_mov_b32 m0, s73
	v_lshl_add_u64 v[226:227], s[50:51], 0, v[148:149]
	s_nop 4
	global_load_lds_dwordx4 v128, s[58:59]
	s_mov_b32 m0, s65
	s_nop 0
	global_load_lds_dwordx4 v150, s[58:59]
	v_lshl_add_u64 v[224:225], s[50:51], 0, v[146:147]
	s_mov_b32 m0, s68
	s_nop 0
	global_load_lds_dwordx4 v[224:225], off
	s_mov_b32 m0, s22
	s_nop 0
	global_load_lds_dwordx4 v[226:227], off
	s_waitcnt vmcnt(8)
	s_waitcnt lgkmcnt(0)
	s_barrier
; #define PG8_STAGE(bufoff, gbase, voff) do { _Pragma("unroll") for (int _i = 0; _i < 2; ++_i) \
;         __builtin_amdgcn_global_load_lds((const unsigned*)((const char*)(gbase) + (voff)[_i]), (LAS unsigned*)(lds + (bufoff) + ldsw + _i * 8192), 16, 0, 0); } while (0)
; #define PG8_LDA(dst, b, h) do { _Pragma("unroll") for (int m = 0; m < 4; ++m) _Pragma("unroll") for (int k = 0; k < 2; ++k) dst[m][k] = *(const LAS bf16x8*)(lds + PG8_SA(b, h) + aoff + m * 2048 + k * 1024); } while (0)
; #define PG8_LDB(dst, b, h) do { _Pragma("unroll") for (int n = 0; n < 2; ++n) _Pragma("unroll") for (int k = 0; k < 2; ++k) dst[n][k] = *(const LAS bf16x8*)(lds + PG8_SB(b, h) + boff + n * 2048 + k * 1024); } while (0)
; #define PG8_MMA(ai, bj, At, Bt) do { __builtin_amdgcn_s_setprio(1); _Pragma("unroll") for (int m = 0; m < 4; ++m) _Pragma("unroll") for (int n = 0; n < 2; ++n) _Pragma("unroll") for (int k = 0; k < 2; ++k) \
;         acc[ai][bj][m][n] = __builtin_amdgcn_mfma_f32_16x16x32_bf16(Bt[n][k], At[m][k], acc[ai][bj][m][n], 0, 0, 0); __builtin_amdgcn_s_setprio(0); } while (0)
; #define PG8_WAIT_V(n) asm volatile("s_waitcnt vmcnt(" #n ")" ::: "memory")
; #define PG8_WAIT_L(n) asm volatile("s_waitcnt lgkmcnt(" #n ")" ::: "memory")
; #define PG8_BAR __builtin_amdgcn_s_barrier()
; #define PG8_SCHED __builtin_amdgcn_sched_barrier(0)
; template <class Epi, class Sched, bool ALIGN_EPI = false, bool SP2 = false>
; __device__ __forceinline__ void gemm_phase(LAS unsigned char* lds, const Gemm g, const Sched& S, const Epi& E) {
;     ...
;             PG8_LDA(At, 0, 1); PG8_STAGE(PG8_SB(0, 0), b2, voffB); PG8_STAGE(PG8_SB(0, 1), b2 + hstep, voffB); PG8_STAGE(PG8_SA(0, 0), a2, voffA);
;             PG8_WAIT_V(8); PG8_WAIT_L(0); PG8_BAR; PG8_MMA(1, 0, At, B0); PG8_MMA(1, 1, At, B1); PG8_BAR; PG8_SCHED;
;             PG8_LDB(B0, 1, 0); PG8_LDB(B1, 1, 1); PG8_SCHED; PG8_LDA(At, 1, 0); PG8_STAGE(PG8_SA(0, 1), a2 + hstep, voffA);
;             PG8_WAIT_V(8); PG8_WAIT_L(0); PG8_BAR; PG8_MMA(0, 0, At, B0); PG8_MMA(0, 1, At, B1); PG8_BAR; PG8_SCHED;
;             PG8_LDA(At, 1, 1); PG8_STAGE(PG8_SB(1, 0), b3, voffB); PG8_STAGE(PG8_SB(1, 1), b3 + hstep, voffB); PG8_STAGE(PG8_SA(1, 0), a3, voffA);
	s_setprio 1
	s_waitcnt lgkmcnt(0)
	v_mfma_f32_16x16x32_bf16 v[60:63], v[64:67], v[180:183], v[60:63]
	v_mfma_f32_16x16x32_bf16 v[56:59], v[72:75], v[180:183], v[56:59]
	v_mfma_f32_16x16x32_bf16 v[44:47], v[64:67], v[188:191], v[44:47]
	v_mfma_f32_16x16x32_bf16 v[40:43], v[72:75], v[188:191], v[40:43]
	v_mfma_f32_16x16x32_bf16 v[28:31], v[64:67], v[208:211], v[28:31]
	v_mfma_f32_16x16x32_bf16 v[24:27], v[72:75], v[208:211], v[24:27]
	v_mfma_f32_16x16x32_bf16 v[12:15], v[64:67], v[216:219], v[12:15]
	v_mfma_f32_16x16x32_bf16 v[8:11], v[72:75], v[216:219], v[8:11]
	v_mfma_f32_16x16x32_bf16 v[60:63], v[68:71], v[184:187], v[60:63]
	v_mfma_f32_16x16x32_bf16 v[56:59], v[80:83], v[184:187], v[56:59]
	v_mfma_f32_16x16x32_bf16 v[44:47], v[68:71], v[192:195], v[44:47]
	v_mfma_f32_16x16x32_bf16 v[40:43], v[80:83], v[192:195], v[40:43]
	v_mfma_f32_16x16x32_bf16 v[28:31], v[68:71], v[212:215], v[28:31]
	v_mfma_f32_16x16x32_bf16 v[24:27], v[80:83], v[212:215], v[24:27]
	v_mfma_f32_16x16x32_bf16 v[12:15], v[68:71], v[220:223], v[12:15]
	v_mfma_f32_16x16x32_bf16 v[8:11], v[80:83], v[220:223], v[8:11]
	s_setprio 0
	s_setprio 1
	v_mfma_f32_16x16x32_bf16 v[52:55], v[156:159], v[180:183], v[52:55]
	v_mfma_f32_16x16x32_bf16 v[48:51], v[172:175], v[180:183], v[48:51]
	v_mfma_f32_16x16x32_bf16 v[36:39], v[156:159], v[188:191], v[36:39]
	v_mfma_f32_16x16x32_bf16 v[32:35], v[172:175], v[188:191], v[32:35]
	v_mfma_f32_16x16x32_bf16 v[20:23], v[156:159], v[208:211], v[20:23]
	v_mfma_f32_16x16x32_bf16 v[16:19], v[172:175], v[208:211], v[16:19]
	v_mfma_f32_16x16x32_bf16 v[4:7], v[156:159], v[216:219], v[4:7]
	v_mfma_f32_16x16x32_bf16 v[0:3], v[172:175], v[216:219], v[0:3]
	v_mfma_f32_16x16x32_bf16 v[52:55], v[164:167], v[184:187], v[52:55]
	v_mfma_f32_16x16x32_bf16 v[48:51], v[176:179], v[184:187], v[48:51]
	v_mfma_f32_16x16x32_bf16 v[36:39], v[164:167], v[192:195], v[36:39]
	v_mfma_f32_16x16x32_bf16 v[32:35], v[176:179], v[192:195], v[32:35]
	v_mfma_f32_16x16x32_bf16 v[20:23], v[164:167], v[212:215], v[20:23]
	v_mfma_f32_16x16x32_bf16 v[16:19], v[176:179], v[212:215], v[16:19]
	v_mfma_f32_16x16x32_bf16 v[4:7], v[164:167], v[220:223], v[4:7]
	v_mfma_f32_16x16x32_bf16 v[0:3], v[176:179], v[220:223], v[0:3]
	s_setprio 0
	s_barrier
	v_or_b32_e32 v64, 0x18000, v163
	v_add_u32_e32 v68, 0x18400, v163
	v_add_u32_e32 v72, 0x18800, v163
	v_add_u32_e32 v80, 0x18c00, v163
	v_or_b32_e32 v156, 0x1c000, v163
	v_add_u32_e32 v164, 0x1c400, v163
	v_add_u32_e32 v172, 0x1c800, v163
	v_add_u32_e32 v176, 0x1cc00, v163
	ds_read_b128 v[64:67], v64
	ds_read_b128 v[68:71], v68
	ds_read_b128 v[72:75], v72
	ds_read_b128 v[80:83], v80
	ds_read_b128 v[156:159], v156
	ds_read_b128 v[164:167], v164
	ds_read_b128 v[172:175], v172
	ds_read_b128 v[176:179], v176
	s_add_u32 s50, s50, 0x40000
	s_addc_u32 s51, s51, 0
	s_mov_b32 m0, s23
	ds_read_b128 v[180:183], v162 offset:32768
	ds_read_b128 v[184:187], v162 offset:33792
	ds_read_b128 v[188:191], v162 offset:34816
	ds_read_b128 v[192:195], v162 offset:35840
	ds_read_b128 v[208:211], v162 offset:36864
	ds_read_b128 v[212:215], v162 offset:37888
	ds_read_b128 v[216:219], v162 offset:38912
	ds_read_b128 v[220:223], v162 offset:39936
	global_load_lds_dwordx4 v146, s[50:51]
	v_lshl_add_u64 v[228:229], s[50:51], 0, v[148:149]
	s_mov_b32 m0, s0
	s_nop 0
	global_load_lds_dwordx4 v[228:229], off
	s_waitcnt vmcnt(8)
	s_waitcnt lgkmcnt(0)
	s_barrier
	s_setprio 1
	s_waitcnt lgkmcnt(0)
	v_mfma_f32_16x16x32_bf16 v[142:145], v[64:67], v[180:183], v[142:145]
	v_mfma_f32_16x16x32_bf16 v[138:141], v[72:75], v[180:183], v[138:141]
	v_mfma_f32_16x16x32_bf16 v[124:127], v[64:67], v[188:191], v[124:127]
	v_mfma_f32_16x16x32_bf16 v[120:123], v[72:75], v[188:191], v[120:123]
	v_mfma_f32_16x16x32_bf16 v[108:111], v[64:67], v[208:211], v[108:111]
	v_mfma_f32_16x16x32_bf16 v[104:107], v[72:75], v[208:211], v[104:107]
	v_mfma_f32_16x16x32_bf16 v[92:95], v[64:67], v[216:219], v[92:95]
	v_mfma_f32_16x16x32_bf16 v[88:91], v[72:75], v[216:219], v[88:91]
	v_mfma_f32_16x16x32_bf16 v[142:145], v[68:71], v[184:187], v[142:145]
	v_mfma_f32_16x16x32_bf16 v[138:141], v[80:83], v[184:187], v[138:141]
	v_mfma_f32_16x16x32_bf16 v[124:127], v[68:71], v[192:195], v[124:127]
	v_mfma_f32_16x16x32_bf16 v[120:123], v[80:83], v[192:195], v[120:123]
	v_mfma_f32_16x16x32_bf16 v[108:111], v[68:71], v[212:215], v[108:111]
	v_mfma_f32_16x16x32_bf16 v[104:107], v[80:83], v[212:215], v[104:107]
	v_mfma_f32_16x16x32_bf16 v[92:95], v[68:71], v[220:223], v[92:95]
	v_mfma_f32_16x16x32_bf16 v[88:91], v[80:83], v[220:223], v[88:91]
	s_setprio 0
	s_setprio 1
	v_mfma_f32_16x16x32_bf16 v[134:137], v[156:159], v[180:183], v[134:137]
	v_mfma_f32_16x16x32_bf16 v[130:133], v[172:175], v[180:183], v[130:133]
	v_mfma_f32_16x16x32_bf16 v[116:119], v[156:159], v[188:191], v[116:119]
	v_mfma_f32_16x16x32_bf16 v[112:115], v[172:175], v[188:191], v[112:115]
	v_mfma_f32_16x16x32_bf16 v[100:103], v[156:159], v[208:211], v[100:103]
	v_mfma_f32_16x16x32_bf16 v[96:99], v[172:175], v[208:211], v[96:99]
	v_mfma_f32_16x16x32_bf16 v[84:87], v[156:159], v[216:219], v[84:87]
	v_mfma_f32_16x16x32_bf16 v[76:79], v[172:175], v[216:219], v[76:79]
	v_mfma_f32_16x16x32_bf16 v[134:137], v[164:167], v[184:187], v[134:137]
	v_mfma_f32_16x16x32_bf16 v[130:133], v[176:179], v[184:187], v[130:133]
	v_mfma_f32_16x16x32_bf16 v[116:119], v[164:167], v[192:195], v[116:119]
	v_mfma_f32_16x16x32_bf16 v[112:115], v[176:179], v[192:195], v[112:115]
	v_mfma_f32_16x16x32_bf16 v[100:103], v[164:167], v[212:215], v[100:103]
	v_mfma_f32_16x16x32_bf16 v[96:99], v[176:179], v[212:215], v[96:99]
	v_mfma_f32_16x16x32_bf16 v[84:87], v[164:167], v[220:223], v[84:87]
	v_mfma_f32_16x16x32_bf16 v[76:79], v[176:179], v[220:223], v[76:79]
	s_setprio 0
	s_barrier
; #define PG8_STAGE(bufoff, gbase, voff) do { _Pragma("unroll") for (int _i = 0; _i < 2; ++_i) \
;         __builtin_amdgcn_global_load_lds((const unsigned*)((const char*)(gbase) + (voff)[_i]), (LAS unsigned*)(lds + (bufoff) + ldsw + _i * 8192), 16, 0, 0); } while (0)
; #define PG8_LDA(dst, b, h) do { _Pragma("unroll") for (int m = 0; m < 4; ++m) _Pragma("unroll") for (int k = 0; k < 2; ++k) dst[m][k] = *(const LAS bf16x8*)(lds + PG8_SA(b, h) + aoff + m * 2048 + k * 1024); } while (0)
; #define PG8_WAIT_V(n) asm volatile("s_waitcnt vmcnt(" #n ")" ::: "memory")
; #define PG8_WAIT_L(n) asm volatile("s_waitcnt lgkmcnt(" #n ")" ::: "memory")
; #define PG8_BAR __builtin_amdgcn_s_barrier()
; template <class Epi, class Sched, bool ALIGN_EPI = false, bool SP2 = false>
; __device__ __forceinline__ void gemm_phase(LAS unsigned char* lds, const Gemm g, const Sched& S, const Epi& E) {
;     ...
;             PG8_LDB(B0, 1, 0); PG8_LDB(B1, 1, 1); PG8_SCHED; PG8_LDA(At, 1, 0); PG8_STAGE(PG8_SA(0, 1), a2 + hstep, voffA);
;             PG8_WAIT_V(8); PG8_WAIT_L(0); PG8_BAR; PG8_MMA(0, 0, At, B0); PG8_MMA(0, 1, At, B1); PG8_BAR; PG8_SCHED;
;             PG8_LDA(At, 1, 1); PG8_STAGE(PG8_SB(1, 0), b3, voffB); PG8_STAGE(PG8_SB(1, 1), b3 + hstep, voffB); PG8_STAGE(PG8_SA(1, 0), a3, voffA);
;             PG8_WAIT_V(8); PG8_WAIT_L(0); PG8_BAR; PG8_MMA(1, 0, At, B0); PG8_MMA(1, 1, At, B1); PG8_BAR; PG8_SCHED;
;     DI void operator()(const f32x4 (&acc)[2][2][4][2], const Unit& u, int wr, int wc, int fr_in, int fq_in) const {
;     ...
;         const int cb = u.pn * 256 + wc * 64;
;         bf16_t* dst; int ld, dcol; const float* gain = nullptr; bool rope = false; float scale = 1.f;
;         if (even) {
;             if (cb < 512) { dst = P; ld = 512; dcol = cb; }
;             else if (cb < 1024) { dst = P + (size_t)NR * 512; ld = 512; dcol = cb - 512; rope = true; scale = QSCALE; }
;             else if (cb < 1152) { dst = P + (size_t)NR * 1024; ld = 128; dcol = cb - 1024; rope = true; }
;             else { dst = P + (size_t)NR * 1152; ld = 128; dcol = cb - 1152; }
;         } else {
;             if (cb < 1024) { dst = P; ld = 1024; dcol = cb; gain = qg; rope = true; scale = QSCALE; }
;             else if (cb < 1280) { dst = P + (size_t)NR * 1024; ld = 256; dcol = cb - 1024; gain = kg; rope = true; }
;             else { dst = P + (size_t)NR * 1280; ld = 256; dcol = cb - 1280; }
	s_mov_b32 m0, s70
	v_lshl_add_u64 v[168:169], v[168:169], 0, s[24:25]
	s_add_u32 s44, s44, 0x40080
	ds_read_b128 v[180:183], v162 offset:49152
	ds_read_b128 v[184:187], v162 offset:50176
	ds_read_b128 v[188:191], v162 offset:51200
	ds_read_b128 v[192:195], v162 offset:52224
	ds_read_b128 v[208:211], v162 offset:53248
	ds_read_b128 v[212:215], v162 offset:54272
	ds_read_b128 v[216:219], v162 offset:55296
	ds_read_b128 v[220:223], v162 offset:56320
	global_load_lds_dwordx4 v[168:169], off
	v_lshl_add_u64 v[168:169], v[196:197], 0, s[24:25]
	s_mov_b32 m0, s71
	s_addc_u32 s45, s45, 0
	global_load_lds_dwordx4 v[168:169], off
	s_mov_b32 m0, s2
	s_nop 0
	s_nop 4
	global_load_lds_dwordx4 v128, s[44:45]
	v_lshl_add_u64 v[168:169], s[44:45], 0, v[150:151]
	s_mov_b32 m0, s26
	s_nop 0
	global_load_lds_dwordx4 v[168:169], off
	v_lshl_add_u64 v[168:169], v[224:225], 0, s[24:25]
	s_mov_b32 m0, s97
	s_nop 0
	global_load_lds_dwordx4 v[168:169], off
	v_lshl_add_u64 v[168:169], v[226:227], 0, s[24:25]
	s_mov_b32 m0, s99
	s_nop 0
	global_load_lds_dwordx4 v[168:169], off
	s_waitcnt vmcnt(8)
	s_waitcnt lgkmcnt(0)
	s_barrier
	s_setprio 1
	s_waitcnt lgkmcnt(0)
	v_mfma_f32_16x16x32_bf16 v[60:63], v[64:67], v[180:183], v[60:63]
	v_mfma_f32_16x16x32_bf16 v[56:59], v[72:75], v[180:183], v[56:59]
	v_mfma_f32_16x16x32_bf16 v[44:47], v[64:67], v[188:191], v[44:47]
	v_mfma_f32_16x16x32_bf16 v[40:43], v[72:75], v[188:191], v[40:43]
	v_mfma_f32_16x16x32_bf16 v[28:31], v[64:67], v[208:211], v[28:31]
	v_mfma_f32_16x16x32_bf16 v[24:27], v[72:75], v[208:211], v[24:27]
	v_mfma_f32_16x16x32_bf16 v[12:15], v[64:67], v[216:219], v[12:15]
	v_mfma_f32_16x16x32_bf16 v[8:11], v[72:75], v[216:219], v[8:11]
	v_mfma_f32_16x16x32_bf16 v[60:63], v[68:71], v[184:187], v[60:63]
	v_mfma_f32_16x16x32_bf16 v[56:59], v[80:83], v[184:187], v[56:59]
	v_mfma_f32_16x16x32_bf16 v[44:47], v[68:71], v[192:195], v[44:47]
	v_mfma_f32_16x16x32_bf16 v[40:43], v[80:83], v[192:195], v[40:43]
	v_mfma_f32_16x16x32_bf16 v[28:31], v[68:71], v[212:215], v[28:31]
	v_mfma_f32_16x16x32_bf16 v[24:27], v[80:83], v[212:215], v[24:27]
	v_mfma_f32_16x16x32_bf16 v[12:15], v[68:71], v[220:223], v[12:15]
	v_mfma_f32_16x16x32_bf16 v[8:11], v[80:83], v[220:223], v[8:11]
	s_setprio 0
	s_setprio 1
	v_mfma_f32_16x16x32_bf16 v[52:55], v[156:159], v[180:183], v[52:55]
	v_mfma_f32_16x16x32_bf16 v[48:51], v[172:175], v[180:183], v[48:51]
	v_mfma_f32_16x16x32_bf16 v[36:39], v[156:159], v[188:191], v[36:39]
	v_mfma_f32_16x16x32_bf16 v[32:35], v[172:175], v[188:191], v[32:35]
	v_mfma_f32_16x16x32_bf16 v[20:23], v[156:159], v[208:211], v[20:23]
	v_mfma_f32_16x16x32_bf16 v[16:19], v[172:175], v[208:211], v[16:19]
	v_mfma_f32_16x16x32_bf16 v[4:7], v[156:159], v[216:219], v[4:7]
	v_mfma_f32_16x16x32_bf16 v[0:3], v[172:175], v[216:219], v[0:3]
	v_mfma_f32_16x16x32_bf16 v[52:55], v[164:167], v[184:187], v[52:55]
	v_mfma_f32_16x16x32_bf16 v[48:51], v[176:179], v[184:187], v[48:51]
	v_mfma_f32_16x16x32_bf16 v[36:39], v[164:167], v[192:195], v[36:39]
	v_mfma_f32_16x16x32_bf16 v[32:35], v[176:179], v[192:195], v[32:35]
	v_mfma_f32_16x16x32_bf16 v[20:23], v[164:167], v[212:215], v[20:23]
	v_mfma_f32_16x16x32_bf16 v[16:19], v[176:179], v[212:215], v[16:19]
	v_mfma_f32_16x16x32_bf16 v[4:7], v[164:167], v[220:223], v[4:7]
	v_mfma_f32_16x16x32_bf16 v[0:3], v[176:179], v[220:223], v[0:3]
	s_setprio 0
	s_barrier
	s_add_i32 s55, s55, 2
	s_add_u32 s42, s42, 0x100
	s_addc_u32 s43, s43, 0
	s_add_u32 s53, s53, 0x100
	s_addc_u32 s54, s54, 0
	s_cmp_gt_u32 s55, 13
	s_cbranch_scc0 .LBB0_334
	s_lshl_b32 s35, s40, 8
	v_readlane_b32 s40, v254, 20
	v_readlane_b32 s41, v254, 21
	v_mov_b32_e32 v168, v161
	v_mov_b32_e32 v167, v160
	s_or_b32 s31, s35, s27
	s_mov_b64 s[42:43], -1
	s_and_b64 vcc, exec, s[40:41]
	s_cbranch_vccz .LBB0_342
	s_cmpk_lt_i32 s31, 0x400
	s_cbranch_scc1 .LBB0_341
	s_cmpk_gt_u32 s35, 0x4ff
	s_mov_b64 s[40:41], -1
	s_cbranch_scc0 .LBB0_339
	s_add_i32 s60, s31, 0xfffffb00
	s_mov_b64 s[40:41], 0
